# loop-top waits made store-aware for gate/up GEMMs (vmcnt 12/14 + 8 dummy loads pre-loop); in_proj epilogue rs loads above prefetch
# baseline (speedup 1.0000x reference)
; __device__ void run_phase(const KP& p_, int ph) {
;     ...
;     int l = (ph - 1) / 12, q = (ph - 1) % 12;
;     const bfr* Wl = W + (size_t)l * W_LAYER;
;     if (q == 2 || q == 8 || (q == 11 && l == 0)) { phase_stat(p); return; }
;     if (q == 11) { phase_final(p); return; }
;     if (q == 4) { phase_pre(p, l); return; }
;     if (q == 5) { phase_seq(p, l); return; }
;     if (q == 6) { phase_mixnorm(p, l); return; }
;     if (q == 0) { gemm_phase<1, NGU, DM>(p, l, hb, Wl + W_GUA); if (l == 0) { plo = 1408; phi = 2112; pfirst = (132 * 22) % p.nblk; } }
;     else if (q == 1) { gemm_phase<2, DM, DFF>(p, l, U, Wl + W_DA); if (l == 0) { plo = 2112; phi = 5440; } else { plo = 7552; phi = 10880; } }
;     else if (q == 3) gemm_phase<3, NINP, DM>(p, l, hb, Wl + W_IN);
;     else if (q == 7) { gemm_phase<2, DM, DM>(p, l, mix, Wl + W_OUT); if (l == 0) { plo = 5440; phi = 6140; } }
;     else if (q == 9) gemm_phase<1, NGU, DM>(p, l, hb, Wl + W_GUB);
;     else { gemm_phase<2, DM, DFF>(p, l, U, Wl + W_DB); if (l == 0) { plo = 6140; phi = 7552; } }
.LBB0_16:
	s_andn2_b64 vcc, exec, s[0:1]
	s_cbranch_vccnz .LBB0_25
	s_cmp_lg_u32 s16, 11
	s_cselect_b64 s[0:1], -1, 0
	s_cmp_eq_u32 s16, 11
	s_cselect_b64 s[2:3], -1, 0
	s_add_i32 s14, s68, 10
	s_cmp_lt_u32 s14, 23
	s_cselect_b64 s[14:15], -1, 0
	s_and_b64 s[20:21], s[14:15], s[2:3]
	s_andn2_b64 vcc, exec, s[20:21]
	v_writelane_b32 v255, s20, 51
	s_nop 1
	v_writelane_b32 v255, s21, 52
	s_cbranch_vccz .LBB0_26
	s_and_b64 vcc, exec, s[0:1]
	s_cbranch_vccz .LBB0_234
	v_writelane_b32 v255, s14, 53
	s_ashr_i32 s93, s92, 31
	s_mul_i32 s0, s92, 0x2a80000
	v_writelane_b32 v255, s15, 54
	s_mul_hi_i32 s1, s92, 0x2a80000
	v_readlane_b32 s2, v255, 45
	v_readlane_b32 s3, v255, 46
	v_writelane_b32 v255, s0, 55
	s_add_u32 s0, s2, s0
	v_writelane_b32 v255, s1, 56
	s_addc_u32 s1, s3, s1
	s_add_u32 s0, s0, 0x16c29000
	v_writelane_b32 v255, s0, 57
	s_addc_u32 s0, s1, 0
	s_add_u32 s36, s2, 0x4329000
	v_writelane_b32 v255, s0, 58
	s_addc_u32 s37, s3, 0
	s_add_u32 s42, s2, 0x12a29000
	v_writelane_b32 v255, s92, 59
	s_addc_u32 s43, s3, 0
	s_cmp_lt_i32 s16, 5
	v_writelane_b32 v255, s93, 60
	s_mov_b64 s[44:45], 0
	v_writelane_b32 v255, s16, 61
	s_cbranch_scc1 .LBB0_257
	s_cmp_gt_i32 s16, 6
	s_cbranch_scc0 .LBB0_272
	s_cmp_gt_i32 s16, 8
	s_mov_b32 s95, 0
	s_cbranch_scc0 .LBB0_289
	s_cmp_eq_u32 s16, 9
	s_mov_b64 s[0:1], 0
	v_readlane_b32 s18, v255, 43
	v_readlane_b32 s19, v255, 44
	s_cbranch_scc0 .LBB0_290
	v_readlane_b32 s2, v255, 42
	v_mov_b32_e32 v0, v156
	s_cmpk_gt_i32 s2, 0xb57
	s_cbranch_scc1 .LBB0_293
; #define STAGE_A(P, BASE, br, kt) STAGE_B(P, BASE, br, kt)
; template <int EPI, int N, int K>
; __device__ __forceinline__ void gemm_phase(const KP& p, int l, const bfr* A, const bfr* Bt) {
;     ...
;   int tid = threadIdx.x; asm volatile("" : "+v"(tid));
;   const int wid = tid >> 6, lane = tid & 63, wr = wid >> 2, wc = wid & 3, fr = lane & 15, fq = lane >> 4;
;   const int nt = K / BK;
;   unsigned so0, so1;
;   { int _r, _c; stage_rc(tid * 16, _r, _c); so0 = (unsigned)(_r * K + _c) * 2u; stage_rc(tid * 16 + 8192, _r, _c); so1 = (unsigned)(_r * K + _c) * 2u; }
;     ...
;   int brow = 0, bcol = 0, pn = 0;
;   if (p.bid < nwg) {
;     TILE_COORDS(p.bid, brow, bcol, pn);
;     STAGE_B(SB(0, 0), Bt, bcol, 0); STAGE_A(SA(0, 0), A, brow, 0);
;     STAGE_B(SB(0, 1), Bt, bcol + HALF, 0); STAGE_A(SA(0, 1), A, brow + HM, 0);
;   }
	s_waitcnt vmcnt(0)
	v_bfe_i32 v3, v0, 27, 1
	v_lshlrev_b32_e32 v136, 4, v0
	v_lshrrev_b32_e32 v3, 22, v3
	v_add_u32_e32 v3, v136, v3
	v_and_b32_e32 v3, 0xfffffc00, v3
	v_sub_u32_e32 v3, v136, v3
	v_lshrrev_b32_e32 v4, 4, v3
	v_bitop3_b32 v3, v4, v3, 32 bitop3:0x6c
	v_ashrrev_i32_e32 v2, 31, v0
	v_ashrrev_i32_e32 v5, 31, v3
	v_lshrrev_b32_e32 v2, 26, v2
	v_lshrrev_b32_e32 v5, 26, v5
	v_add_u32_e32 v2, v0, v2
	v_add_u32_e32 v5, v3, v5
	v_ashrrev_i32_e32 v2, 6, v2
	v_lshrrev_b32_e32 v6, 6, v5
	v_and_b32_e32 v5, 0xc0, v5
	v_readlane_b32 s2, v255, 57
	v_lshlrev_b32_e32 v4, 3, v2
	v_lshlrev_b32_e32 v2, 5, v2
	v_sub_u32_e32 v3, v3, v5
	s_add_u32 s33, s2, 0x1a00000
	v_readlane_b32 s2, v255, 58
	v_and_b32_e32 v4, 0x1ffff0, v4
	v_and_b32_e32 v2, 32, v2
	v_ashrrev_i16_sdwa v3, v163, sext(v3) dst_sel:DWORD dst_unused:UNUSED_PAD src0_sel:DWORD src1_sel:BYTE_0
	v_readlane_b32 s82, v255, 42
	s_addc_u32 s72, s2, 0
	v_add_u32_sdwa v2, v2, sext(v3) dst_sel:DWORD dst_unused:UNUSED_PAD src0_sel:DWORD src1_sel:WORD_0
	v_add_lshl_u32 v3, v6, v4, 11
	s_ashr_i32 s2, s82, 31
	v_lshl_add_u32 v137, v2, 1, v3
	v_add_u32_e32 v2, 0x2000, v136
	s_lshr_b32 s2, s2, 29
	v_ashrrev_i32_e32 v3, 31, v2
	s_add_i32 s2, s82, s2
	v_lshrrev_b32_e32 v3, 22, v3
	s_ashr_i32 s3, s2, 3
	s_and_b32 s2, s2, -8
	v_add_u32_e32 v3, v2, v3
	s_sub_i32 s2, s82, s2
	v_ashrrev_i32_e32 v3, 10, v3
	s_cmp_lt_i32 s2, 0
	s_movk_i32 s14, 0x16c
	v_mul_i32_i24_e32 v4, 0x400, v3
	s_cselect_b32 s14, s14, 0x16b
	v_sub_u32_e32 v2, v2, v4
	s_mul_i32 s2, s14, s2
	v_lshrrev_b32_e32 v4, 4, v2
	s_add_i32 s2, s2, s3
	v_bitop3_b32 v2, v4, v2, 32 bitop3:0x6c
	s_mul_hi_i32 s3, s2, 0x2e8ba2e9
	v_ashrrev_i32_e32 v5, 31, v2
	s_lshr_b32 s14, s3, 31
	s_ashr_i32 s3, s3, 5
	v_lshrrev_b32_e32 v5, 26, v5
	s_add_i32 s3, s3, s14
	v_add_u32_e32 v5, v2, v5
	s_lshl_b32 s14, s3, 3
	v_lshrrev_b32_e32 v6, 6, v5
	v_and_b32_e32 v5, 0xc0, v5
	s_sub_i32 s15, 0x84, s14
	v_lshlrev_b32_e32 v4, 3, v3
	v_lshlrev_b32_e32 v3, 5, v3
	v_sub_u32_e32 v2, v2, v5
	s_min_u32 s15, s15, 8
	s_mulk_i32 s3, 0xb0
	v_and_b32_e32 v4, 0x1ffff0, v4
	v_and_b32_e32 v3, 32, v3
	v_ashrrev_i16_sdwa v2, v163, sext(v2) dst_sel:DWORD dst_unused:UNUSED_PAD src0_sel:DWORD src1_sel:BYTE_0
	s_sub_i32 s38, s2, s3
	v_cvt_f32_ubyte0_e32 v5, s15
	v_add_u32_sdwa v2, v3, sext(v2) dst_sel:DWORD dst_unused:UNUSED_PAD src0_sel:DWORD src1_sel:WORD_0
	v_add_lshl_u32 v3, v6, v4, 11
	v_cvt_f32_i32_e32 v4, s38
	v_rcp_iflag_f32_e32 v6, v5
	v_lshl_add_u32 v138, v2, 1, v3
	s_ashr_i32 s2, s38, 30
	s_or_b32 s39, s2, 1
	v_mul_f32_e32 v2, v4, v6
	v_trunc_f32_e32 v2, v2
	v_fma_f32 v3, -v2, v5, v4
	v_cvt_i32_f32_e32 v2, v2
	v_cmp_ge_f32_e64 s[2:3], |v3|, v5
	s_and_b64 s[2:3], s[2:3], exec
	s_cselect_b32 s2, s39, 0
	v_readfirstlane_b32 s3, v2
	s_add_i32 s2, s3, s2
	s_sext_i32_i16 s3, s2
	s_mul_i32 s2, s2, s15
	s_sub_i32 s2, s38, s2
	s_sext_i32_i16 s2, s2
	s_lshl_b32 s78, s3, 8
	s_add_i32 s14, s14, s2
	s_ashr_i32 s79, s78, 31
	v_readlane_b32 s15, v255, 41
	s_lshl_b32 s76, s14, 8
	s_lshl_b64 s[2:3], s[78:79], 11
	v_add_u32_e32 v139, s15, v136
	s_add_u32 s2, s33, s2
	v_readfirstlane_b32 s14, v139
	v_add_u32_e32 v140, 0x2000, v139
	s_addc_u32 s3, s72, s3
	v_mov_b32_e32 v2, v138
	v_mov_b32_e32 v3, v137
	s_mov_b32 m0, s14
	v_readfirstlane_b32 s14, v140
	s_ashr_i32 s77, s76, 31
	global_load_lds_dwordx4 v3, s[2:3]
	s_mov_b32 m0, s14
	v_readlane_b32 s16, v255, 45
	global_load_lds_dwordx4 v2, s[2:3]
	s_lshl_b64 s[2:3], s[76:77], 11
	v_add_u32_e32 v141, 0, v136
	v_readlane_b32 s17, v255, 46
	s_add_u32 s2, s16, s2
	v_readfirstlane_b32 s14, v141
	v_add_u32_e32 v142, 0x2000, v141
	s_addc_u32 s3, s17, s3
	v_mov_b32_e32 v2, v138
	v_mov_b32_e32 v3, v137
	s_mov_b32 m0, s14
	v_readfirstlane_b32 s14, v142
	v_add_u32_e32 v143, s66, v136
	global_load_lds_dwordx4 v3, s[2:3]
	s_mov_b32 m0, s14
	v_readfirstlane_b32 s14, v143
	global_load_lds_dwordx4 v2, s[2:3]
	s_or_b32 s2, s78, 0x80
	s_ashr_i32 s3, s2, 31
	s_lshl_b64 s[2:3], s[2:3], 11
	s_add_u32 s2, s33, s2
	v_add_u32_e32 v144, 0x2000, v143
	s_addc_u32 s3, s72, s3
	v_mov_b32_e32 v2, v138
	v_mov_b32_e32 v3, v137
	s_mov_b32 m0, s14
	v_readfirstlane_b32 s14, v144
	v_add_u32_e32 v145, 0x4000, v141
	global_load_lds_dwordx4 v3, s[2:3]
	s_mov_b32 m0, s14
	v_readfirstlane_b32 s14, v145
	global_load_lds_dwordx4 v2, s[2:3]
	s_or_b32 s2, s76, 0x80
	s_ashr_i32 s3, s2, 31
	s_lshl_b64 s[2:3], s[2:3], 11
	s_add_u32 s2, s16, s2
	v_add_u32_e32 v146, 0x6000, v141
	s_addc_u32 s3, s17, s3
	v_mov_b32_e32 v2, v138
	v_mov_b32_e32 v3, v137
	s_mov_b32 m0, s14
	v_readfirstlane_b32 s14, v146
	s_waitcnt lgkmcnt(0)
	v_lshlrev_b32_e32 v8, 2, v0
	global_load_lds_dwordx4 v3, s[2:3]
	s_mov_b32 m0, s14
	v_and_b32_e32 v3, 15, v0
	global_load_lds_dwordx4 v2, s[2:3]
	v_and_b32_e32 v2, 48, v0
	v_lshlrev_b32_e32 v7, 6, v3
	v_and_b32_e32 v8, 32, v8
	v_bitop3_b32 v7, v2, v8, v7 bitop3:0x36
	v_readlane_b32 s2, v254, 48
	v_bfe_u32 v4, v0, 6, 2
	v_ashrrev_i32_e32 v5, 8, v0
	v_add_u32_e32 v11, s2, v7
	v_readlane_b32 s2, v254, 49
	v_lshlrev_b32_e32 v13, 13, v5
	v_cmp_eq_u32_e64 s[38:39], 1, v5
	v_add_u32_e32 v12, s2, v7
	s_movk_i32 s2, 0x100
	v_cmp_gt_u32_e64 s[40:41], s2, v0
	v_lshlrev_b32_e32 v0, 6, v0
	s_movk_i32 s2, 0x3c0
	v_and_or_b32 v0, v0, s2, v2
	v_xad_u32 v8, v0, v8, 0
	v_lshlrev_b32_e32 v0, 6, v4
	v_lshlrev_b32_e32 v6, 12, v4
	v_add_u32_e32 v9, s15, v7
	v_add_u32_e32 v10, s66, v7
	v_lshl_or_b32 v147, v5, 6, v3
	v_add_u32_e32 v7, 0, v7
	v_or_b32_e32 v14, 0x800, v13
	v_or_b32_e32 v15, 0x1000, v13
	v_or_b32_e32 v16, 0x1800, v13
	v_lshl_add_u64 v[4:5], s[36:37], 0, v[0:1]
	v_mov_b32_e32 v3, v1
	s_add_u32 s46, s16, 0x4200000
	v_lshl_add_u64 v[130:131], v[4:5], 0, v[2:3]
	s_addc_u32 s47, s17, 0
	v_add_u32_e32 v148, 0x8000, v141
	v_add_u32_e32 v149, 0xa000, v141
	v_add_u32_e32 v150, v9, v6
	v_add_u32_e32 v151, v7, v13
	v_add_u32_e32 v152, v8, v14
	v_add_u32_e32 v153, v8, v15
	v_add_u32_e32 v154, v8, v16
	v_add_u32_e32 v155, v10, v6
	v_add_u32_e32 v174, v11, v6
	v_add_u32_e32 v175, v12, v6
	global_load_dword v253, v[130:131], off
	global_load_dword v253, v[130:131], off
	global_load_dword v253, v[130:131], off
	global_load_dword v253, v[130:131], off
	global_load_dword v253, v[130:131], off
	global_load_dword v253, v[130:131], off
	global_load_dword v253, v[130:131], off
	global_load_dword v253, v[130:131], off
	s_branch .LBB0_236

; #define STAGE_A(P, BASE, br, kt) STAGE_B(P, BASE, br, kt)
; #define WAIT_V(n) asm volatile("s_waitcnt vmcnt(" #n ")" ::: "memory")
; #define BAR __builtin_amdgcn_s_barrier()
; template <int EPI, int N, int K>
; __device__ __forceinline__ void gemm_phase(const KP& p, int l, const bfr* A, const bfr* Bt) {
;     ...
;   for (int Lt = p.bid; Lt < nwg; Lt += p.nblk) {
;     f32x4 acc[2][2][4][2];
; #pragma unroll
;     for (int a = 0; a < 2; ++a)
; #pragma unroll
;       for (int b = 0; b < 2; ++b)
; #pragma unroll
;         for (int m = 0; m < 4; ++m)
; #pragma unroll
;           for (int n = 0; n < 2; ++n) acc[a][b][m][n] = f32x4{0.f, 0.f, 0.f, 0.f};
;     bf16x8 At[4][2], B0[2][2], B1[2][2];
;     if (wr == 1) BAR;
;     WAIT_V(4); BAR;
;     STAGE_B(SB(1, 0), Bt, bcol, 1); STAGE_A(SA(1, 0), A, brow, 1); STAGE_B(SB(1, 1), Bt, bcol + HALF, 1);
;     WAIT_V(6); BAR;
.LBB0_238:
	s_or_b64 exec, exec, s[50:51]
	s_ashr_i32 s79, s78, 31
	s_lshl_b64 s[2:3], s[78:79], 11
	s_add_u32 s14, s33, s2
	v_readlane_b32 s50, v254, 48
	s_addc_u32 s15, s72, s3
	v_mov_b32_e32 v2, v138
	v_mov_b32_e32 v0, v137
	v_add_u32_e32 v132, s50, v136
	s_waitcnt vmcnt(12)
	s_barrier
	s_mov_b64 s[56:57], 0x80
	v_lshl_add_u64 v[4:5], s[14:15], 0, v[0:1]
	v_readfirstlane_b32 s50, v132
	v_mov_b32_e32 v3, v1
	v_add_u32_e32 v133, 0x2000, v132
	s_ashr_i32 s77, s76, 31
	v_lshl_add_u64 v[4:5], v[4:5], 0, s[56:57]
	s_mov_b32 m0, s50
	v_lshl_add_u64 v[2:3], s[14:15], 0, v[2:3]
	v_readfirstlane_b32 s14, v133
	s_lshl_b64 s[50:51], s[76:77], 11
	v_readlane_b32 s16, v255, 45
	global_load_lds_dwordx4 v[4:5], off
	v_lshl_add_u64 v[2:3], v[2:3], 0, s[56:57]
	s_mov_b32 m0, s14
	v_readlane_b32 s17, v255, 46
	s_add_u32 s14, s16, s50
	global_load_lds_dwordx4 v[2:3], off
	s_addc_u32 s15, s17, s51
	v_mov_b32_e32 v2, v138
	v_mov_b32_e32 v0, v137
	v_readfirstlane_b32 s52, v148
	v_lshl_add_u64 v[4:5], s[14:15], 0, v[0:1]
	v_mov_b32_e32 v3, v1
	v_lshl_add_u64 v[4:5], v[4:5], 0, s[56:57]
	s_mov_b32 m0, s52
	v_lshl_add_u64 v[2:3], s[14:15], 0, v[2:3]
	v_readfirstlane_b32 s14, v149
	global_load_lds_dwordx4 v[4:5], off
	s_mov_b32 m0, s14
	s_or_b32 s14, s78, 0x80
	s_ashr_i32 s15, s14, 31
	s_lshl_b64 s[14:15], s[14:15], 11
	v_lshl_add_u64 v[2:3], v[2:3], 0, s[56:57]
	s_add_u32 s14, s33, s14
	v_readlane_b32 s52, v254, 49
	global_load_lds_dwordx4 v[2:3], off
	s_addc_u32 s15, s72, s15
	v_mov_b32_e32 v2, v138
	v_mov_b32_e32 v0, v137
	v_add_u32_e32 v134, s52, v136
	v_mov_b32_e32 v3, v1
	v_lshl_add_u64 v[4:5], s[14:15], 0, v[0:1]
	v_readfirstlane_b32 s52, v134
	v_add_u32_e32 v135, 0x2000, v134
	v_lshl_add_u64 v[4:5], v[4:5], 0, s[56:57]
	s_mov_b32 m0, s52
	v_lshl_add_u64 v[2:3], s[14:15], 0, v[2:3]
	v_readfirstlane_b32 s14, v135
	global_load_lds_dwordx4 v[4:5], off
	v_lshl_add_u64 v[2:3], v[2:3], 0, s[56:57]
	s_mov_b32 m0, s14
	s_mul_i32 s14, s92, 0x2a80000
	global_load_lds_dwordx4 v[2:3], off
	s_waitcnt vmcnt(14)
	s_add_u32 s2, s14, s2
	s_mul_hi_i32 s14, s92, 0x2a80000
	v_mov_b32_e32 v2, 0
	s_addc_u32 s3, s14, s3
	s_mov_b32 s14, -2
	s_mov_b64 s[52:53], s[16:17]
	v_mov_b32_e32 v3, v2
	v_mov_b32_e32 v4, v2
	v_mov_b32_e32 v5, v2
	v_mov_b32_e32 v6, v2
	v_mov_b32_e32 v7, v2
	v_mov_b32_e32 v8, v2
	v_mov_b32_e32 v9, v2
	v_mov_b32_e32 v10, v2
	v_mov_b32_e32 v11, v2
	v_mov_b32_e32 v12, v2
	v_mov_b32_e32 v13, v2
	v_mov_b32_e32 v14, v2
	v_mov_b32_e32 v15, v2
	v_mov_b32_e32 v16, v2
	v_mov_b32_e32 v17, v2
	v_mov_b32_e32 v18, v2
	v_mov_b32_e32 v19, v2
	v_mov_b32_e32 v20, v2
	v_mov_b32_e32 v21, v2
	v_mov_b32_e32 v22, v2
	v_mov_b32_e32 v23, v2
	v_mov_b32_e32 v24, v2
	v_mov_b32_e32 v25, v2
	v_mov_b32_e32 v26, v2
	v_mov_b32_e32 v27, v2
	v_mov_b32_e32 v28, v2
	v_mov_b32_e32 v29, v2
	v_mov_b32_e32 v30, v2
	v_mov_b32_e32 v31, v2
	v_mov_b32_e32 v32, v2
	v_mov_b32_e32 v33, v2
	v_mov_b32_e32 v34, v2
	v_mov_b32_e32 v35, v2
	v_mov_b32_e32 v36, v2
	v_mov_b32_e32 v37, v2
	v_mov_b32_e32 v38, v2
	v_mov_b32_e32 v39, v2
	v_mov_b32_e32 v40, v2
	v_mov_b32_e32 v41, v2
	v_mov_b32_e32 v42, v2
	v_mov_b32_e32 v43, v2
	v_mov_b32_e32 v44, v2
	v_mov_b32_e32 v45, v2
	v_mov_b32_e32 v46, v2
	v_mov_b32_e32 v47, v2
	v_mov_b32_e32 v48, v2
	v_mov_b32_e32 v49, v2
	v_mov_b32_e32 v50, v2
	v_mov_b32_e32 v51, v2
	v_mov_b32_e32 v52, v2
	v_mov_b32_e32 v53, v2
	v_mov_b32_e32 v54, v2
	v_mov_b32_e32 v55, v2
	v_mov_b32_e32 v56, v2
	v_mov_b32_e32 v57, v2
	v_mov_b32_e32 v58, v2
	v_mov_b32_e32 v59, v2
	v_mov_b32_e32 v60, v2
	v_mov_b32_e32 v61, v2
	v_mov_b32_e32 v62, v2
	v_mov_b32_e32 v63, v2
	v_mov_b32_e32 v64, v2
	v_mov_b32_e32 v65, v2
	v_mov_b32_e32 v66, v2
	v_mov_b32_e32 v67, v2
	v_mov_b32_e32 v68, v2
	v_mov_b32_e32 v69, v2
	v_mov_b32_e32 v70, v2
	v_mov_b32_e32 v71, v2
	v_mov_b32_e32 v72, v2
	v_mov_b32_e32 v73, v2
	v_mov_b32_e32 v74, v2
	v_mov_b32_e32 v75, v2
	v_mov_b32_e32 v76, v2
	v_mov_b32_e32 v77, v2
	v_mov_b32_e32 v78, v2
	v_mov_b32_e32 v79, v2
	v_mov_b32_e32 v80, v2
	v_mov_b32_e32 v81, v2
	v_mov_b32_e32 v82, v2
	v_mov_b32_e32 v83, v2
	v_mov_b32_e32 v84, v2
	v_mov_b32_e32 v85, v2
	v_mov_b32_e32 v86, v2
	v_mov_b32_e32 v87, v2
	v_mov_b32_e32 v88, v2
	v_mov_b32_e32 v89, v2
	v_mov_b32_e32 v90, v2
	v_mov_b32_e32 v91, v2
	v_mov_b32_e32 v92, v2
	v_mov_b32_e32 v93, v2
	v_mov_b32_e32 v94, v2
	v_mov_b32_e32 v95, v2
	v_mov_b32_e32 v96, v2
	v_mov_b32_e32 v97, v2
	v_mov_b32_e32 v98, v2
	v_mov_b32_e32 v99, v2
	v_mov_b32_e32 v100, v2
	v_mov_b32_e32 v101, v2
	v_mov_b32_e32 v102, v2
	v_mov_b32_e32 v103, v2
	v_mov_b32_e32 v104, v2
	v_mov_b32_e32 v105, v2
	v_mov_b32_e32 v106, v2
	v_mov_b32_e32 v107, v2
	v_mov_b32_e32 v108, v2
	v_mov_b32_e32 v109, v2
	v_mov_b32_e32 v110, v2
	v_mov_b32_e32 v111, v2
	v_mov_b32_e32 v112, v2
	v_mov_b32_e32 v113, v2
	v_mov_b32_e32 v114, v2
	v_mov_b32_e32 v115, v2
	v_mov_b32_e32 v116, v2
	v_mov_b32_e32 v117, v2
	v_mov_b32_e32 v118, v2
	v_mov_b32_e32 v119, v2
	v_mov_b32_e32 v120, v2
	v_mov_b32_e32 v121, v2
	v_mov_b32_e32 v122, v2
	v_mov_b32_e32 v123, v2
	v_mov_b32_e32 v124, v2
	v_mov_b32_e32 v125, v2
	v_mov_b32_e32 v126, v2
	v_mov_b32_e32 v127, v2
	v_mov_b32_e32 v128, v2
	v_mov_b32_e32 v129, v2
	s_mov_b64 s[56:57], 0x18629100
	s_mov_b64 s[58:59], 0x18669100
	s_mov_b64 s[60:61], 0x18629180
	s_mov_b64 s[64:65], 0x18669180
	s_barrier

; #define STAGE_A(P, BASE, br, kt) STAGE_B(P, BASE, br, kt)
; template <int EPI, int N, int K>
; __device__ __forceinline__ void gemm_phase(const KP& p, int l, const bfr* A, const bfr* Bt) {
;     ...
;     if (Lt + p.nblk < nwg) {
;       TILE_COORDS(Lt + p.nblk, brow, bcol, pn);
;       STAGE_B(SB(0, 0), Bt, bcol, 0); STAGE_A(SA(0, 0), A, brow, 0);
;       STAGE_B(SB(0, 1), Bt, bcol + HALF, 0); STAGE_A(SA(0, 1), A, brow + HM, 0);
;     }
;     ...
;           int row = erow + ai * HM + wr * 64 + m * 16 + fr;
;           float r = rs[row];
.LBB0_863:
	s_or_b64 exec, exec, s[46:47]
	v_add_u32_e32 v230, s0, v150
	v_ashrrev_i32_e32 v231, 31, v230
	v_lshl_add_u64 v[230:231], v[230:231], 2, s[50:51]
	global_load_dword v222, v[230:231], off
	global_load_dword v223, v[230:231], off offset:64
	global_load_dword v224, v[230:231], off offset:128
	global_load_dword v225, v[230:231], off offset:192
	global_load_dword v226, v[230:231], off offset:512
	global_load_dword v227, v[230:231], off offset:576
	global_load_dword v228, v[230:231], off offset:640
	global_load_dword v229, v[230:231], off offset:704
	v_readlane_b32 s14, v255, 43
	s_add_i32 s87, s87, s14
	s_cmpk_gt_i32 s87, 0x7bb
	s_cselect_b64 s[74:75], -1, 0
	s_and_b64 vcc, exec, s[74:75]
	s_mov_b32 s76, s0
	s_mov_b32 s78, s44
	s_mov_b32 s14, s2
	v_readlane_b32 s15, v255, 44
	s_cbranch_vccnz .Lepi3_nonext
	s_ashr_i32 s1, s87, 31
	s_lshr_b32 s1, s1, 29
	s_add_i32 s1, s87, s1
	s_and_b32 s3, s1, -8
	s_sub_i32 s3, s87, s3
	s_cmp_gt_i32 s3, 3
	s_mov_b64 s[46:47], -1
	s_cbranch_scc0 .LBB0_866
	s_mul_i32 s14, s3, 0xf7
	s_add_i32 s14, s14, 4
	s_mov_b64 s[46:47], 0

; template <int EPI, int N, int K>
; __device__ __forceinline__ void gemm_phase(const KP& p, int l, const bfr* A, const bfr* Bt) {
;     ...
;           int row = erow + ai * HM + wr * 64 + m * 16 + fr;
;           float r = rs[row];
;           if (epn < 14) {
;             float* cdst = nullptr;
;             bfr* tdst = nullptr;
;             if (ecol >= 512 && ecol < 1536) {
;               { int cid, tl;
;                 if (row < SROW0) { int s = row / PROW, pos = row % PROW; cid = s * 65 + (pos >> 6); tl = (pos & 63) - 61; }
;                 else { int rr = row - SROW0; cid = 520 + (rr >> 6); tl = (rr & 63) - 61; }
;                 if (tl >= 0) tdst = (bfr*)(p.ws + OFF_TAILS) + ((size_t)cid * 3 + tl) * 1024; }
;               if (row < SROW0) { int s = row / PROW, tl = row % PROW - (PLEN - 3); if (tl >= 0 && tl < 3) cdst = p.out + O_CP + ((size_t)(l * 8 + s) * 3 + tl) * 1024; }
;               else { int s = (row - SROW0) >> 6, tl = ((row - SROW0) & 63) - 61; if (tl >= 0) cdst = p.out + O_CS + ((size_t)(l * 8 + s) * 3 + tl) * 1024; }
;             }
; #pragma unroll
;             for (int bj = 0; bj < 2; ++bj) {
;               int col = ecol + bj * HALF + wc * 32 + fq * 8;
;               float v[8];
; #pragma unroll
;               for (int n = 0; n < 2; ++n)
; #pragma unroll
;                 for (int jj = 0; jj < 2; ++jj) {
;                   f32v2_t t2 = f32v2_t{acc[ai][bj][m][n][2 * jj], acc[ai][bj][m][n][2 * jj + 1]} * r;
;                   v[n * 4 + 2 * jj] = t2.x; v[n * 4 + 2 * jj + 1] = t2.y;
;                 }
;               u32x4 pk; pk[0] = pack2(v[0], v[1]); pk[1] = pack2(v[2], v[3]); pk[2] = pack2(v[4], v[5]); pk[3] = pack2(v[6], v[7]);
;               *(u32x4*)(proj + (size_t)row * NIN + col) = pk;
;               if (cdst) { *(float4*)(cdst + col - 512) = make_float4(v[0], v[1], v[2], v[3]); *(float4*)(cdst + col - 512 + 4) = make_float4(v[4], v[5], v[6], v[7]); }
;               if (tdst) *(u32x4*)(tdst + col - 512) = pk;
;             }
;           } else {
;             if (wc == 0 && fq == 0) {
;               *(float4*)(dtb + (size_t)row * 8) = make_float4(acc[ai][0][m][0][0] * r, acc[ai][0][m][0][1] * r, acc[ai][0][m][0][2] * r, acc[ai][0][m][0][3] * r);
;               *(float4*)(dtb + (size_t)row * 8 + 4) = make_float4(acc[ai][0][m][1][0] * r, acc[ai][0][m][1][1] * r, acc[ai][0][m][1][2] * r, acc[ai][0][m][1][3] * r);
.LBB0_869:
	v_add_u32_e32 v136, s0, v150
	v_ashrrev_i32_e32 v137, 31, v136
	v_lshl_add_u64 v[130:131], v[136:137], 2, s[50:51]
	s_waitcnt vmcnt(8)
	v_mov_b32_e32 v138, v222
	s_cmp_gt_i32 s2, 13
	s_cselect_b64 s[80:81], -1, 0
	s_add_i32 s1, s44, 0xfffffe00
	s_cmpk_lt_u32 s1, 0x400
	s_cselect_b64 s[46:47], -1, 0
	s_mov_b64 s[82:83], -1
	s_and_b64 vcc, exec, s[80:81]
	s_cbranch_vccz .LBB0_873
	s_and_saveexec_b64 s[82:83], s[42:43]
	s_cbranch_execz .LBB0_872
	v_lshlrev_b64 v[130:131], 5, v[136:137]
	v_lshl_add_u64 v[134:135], s[52:53], 0, v[130:131]
	v_pk_mul_f32 v[130:131], v[126:127], v[138:139] op_sel_hi:[1,0]
	v_pk_mul_f32 v[132:133], v[128:129], v[138:139] op_sel_hi:[1,0]
	global_store_dwordx4 v[134:135], v[130:133], off
	s_nop 1
	v_pk_mul_f32 v[130:131], v[122:123], v[138:139] op_sel_hi:[1,0]
	v_pk_mul_f32 v[132:133], v[124:125], v[138:139] op_sel_hi:[1,0]
	global_store_dwordx4 v[134:135], v[130:133], off offset:16

; __device__ __forceinline__ unsigned pack2(float a, float b) { f32v2_t v = {a, b}; bf16v2_t r = __builtin_convertvector(v, bf16v2_t); return __builtin_bit_cast(unsigned, r); }
; template <int EPI, int N, int K>
; __device__ __forceinline__ void gemm_phase(const KP& p, int l, const bfr* A, const bfr* Bt) {
;     ...
; #pragma unroll
;             for (int bj = 0; bj < 2; ++bj) {
;               int col = ecol + bj * HALF + wc * 32 + fq * 8;
;               float v[8];
; #pragma unroll
;               for (int n = 0; n < 2; ++n)
; #pragma unroll
;                 for (int jj = 0; jj < 2; ++jj) {
;                   f32v2_t t2 = f32v2_t{acc[ai][bj][m][n][2 * jj], acc[ai][bj][m][n][2 * jj + 1]} * r;
;                   v[n * 4 + 2 * jj] = t2.x; v[n * 4 + 2 * jj + 1] = t2.y;
;                 }
;               u32x4 pk; pk[0] = pack2(v[0], v[1]); pk[1] = pack2(v[2], v[3]); pk[2] = pack2(v[4], v[5]); pk[3] = pack2(v[6], v[7]);
;               *(u32x4*)(proj + (size_t)row * NIN + col) = pk;
;               if (cdst) { *(float4*)(cdst + col - 512) = make_float4(v[0], v[1], v[2], v[3]); *(float4*)(cdst + col - 512 + 4) = make_float4(v[4], v[5], v[6], v[7]); }
;               if (tdst) *(u32x4*)(tdst + col - 512) = pk;
;             }
.LBB0_890:
	v_mov_b64_e32 v[130:131], s[36:37]
	s_movk_i32 s0, 0x1c00
	v_mad_i64_i32 v[144:145], s[0:1], v136, s0, v[130:131]
	v_pk_mul_f32 v[130:131], v[126:127], v[138:139] op_sel_hi:[1,0]
	v_pk_mul_f32 v[132:133], v[128:129], v[138:139] op_sel_hi:[1,0]
	v_pk_mul_f32 v[126:127], v[122:123], v[138:139] op_sel_hi:[1,0]
	v_pk_mul_f32 v[128:129], v[124:125], v[138:139] op_sel_hi:[1,0]
	v_ashrrev_i32_e32 v135, 31, v134
	v_cmp_ne_u64_e32 vcc, 0, v[142:143]
	v_cvt_pk_bf16_f32 v122, v130, v131
	v_cvt_pk_bf16_f32 v123, v132, v133
	v_cvt_pk_bf16_f32 v124, v126, v127
	v_cvt_pk_bf16_f32 v125, v128, v129
	v_lshl_add_u64 v[144:145], v[134:135], 1, v[144:145]
	v_lshl_add_u64 v[142:143], v[134:135], 2, v[142:143]
	global_store_dwordx4 v[144:145], v[122:125], off
	s_and_saveexec_b64 s[0:1], vcc
	s_cbranch_execz .LBB0_892
	global_store_dwordx4 v[142:143], v[130:133], off offset:-2048
	global_store_dwordx4 v[142:143], v[126:129], off offset:-2032

; template <int EPI, int N, int K>
; __device__ __forceinline__ void gemm_phase(const KP& p, int l, const bfr* A, const bfr* Bt) {
;     ...
;           int row = erow + ai * HM + wr * 64 + m * 16 + fr;
;           float r = rs[row];
;           if (epn < 14) {
;             float* cdst = nullptr;
;             bfr* tdst = nullptr;
;             if (ecol >= 512 && ecol < 1536) {
;               { int cid, tl;
;                 if (row < SROW0) { int s = row / PROW, pos = row % PROW; cid = s * 65 + (pos >> 6); tl = (pos & 63) - 61; }
;                 else { int rr = row - SROW0; cid = 520 + (rr >> 6); tl = (rr & 63) - 61; }
;                 if (tl >= 0) tdst = (bfr*)(p.ws + OFF_TAILS) + ((size_t)cid * 3 + tl) * 1024; }
;               if (row < SROW0) { int s = row / PROW, tl = row % PROW - (PLEN - 3); if (tl >= 0 && tl < 3) cdst = p.out + O_CP + ((size_t)(l * 8 + s) * 3 + tl) * 1024; }
;               else { int s = (row - SROW0) >> 6, tl = ((row - SROW0) & 63) - 61; if (tl >= 0) cdst = p.out + O_CS + ((size_t)(l * 8 + s) * 3 + tl) * 1024; }
;             }
; #pragma unroll
;             for (int bj = 0; bj < 2; ++bj) {
;               int col = ecol + bj * HALF + wc * 32 + fq * 8;
;               float v[8];
; #pragma unroll
;               for (int n = 0; n < 2; ++n)
; #pragma unroll
;                 for (int jj = 0; jj < 2; ++jj) {
;                   f32v2_t t2 = f32v2_t{acc[ai][bj][m][n][2 * jj], acc[ai][bj][m][n][2 * jj + 1]} * r;
;                   v[n * 4 + 2 * jj] = t2.x; v[n * 4 + 2 * jj + 1] = t2.y;
;                 }
;               u32x4 pk; pk[0] = pack2(v[0], v[1]); pk[1] = pack2(v[2], v[3]); pk[2] = pack2(v[4], v[5]); pk[3] = pack2(v[6], v[7]);
;               *(u32x4*)(proj + (size_t)row * NIN + col) = pk;
;               if (cdst) { *(float4*)(cdst + col - 512) = make_float4(v[0], v[1], v[2], v[3]); *(float4*)(cdst + col - 512 + 4) = make_float4(v[4], v[5], v[6], v[7]); }
;               if (tdst) *(u32x4*)(tdst + col - 512) = pk;
;             }
;           } else {
;             if (wc == 0 && fq == 0) {
;               *(float4*)(dtb + (size_t)row * 8) = make_float4(acc[ai][0][m][0][0] * r, acc[ai][0][m][0][1] * r, acc[ai][0][m][0][2] * r, acc[ai][0][m][0][3] * r);
;               *(float4*)(dtb + (size_t)row * 8 + 4) = make_float4(acc[ai][0][m][1][0] * r, acc[ai][0][m][1][1] * r, acc[ai][0][m][1][2] * r, acc[ai][0][m][1][3] * r);
.LBB0_899:
	s_nop 0
	v_add_u32_e32 v114, 16, v136
	v_ashrrev_i32_e32 v115, 31, v114
	v_lshl_add_u64 v[116:117], v[114:115], 2, s[50:51]
	v_mov_b32_e32 v118, v223
	v_cndmask_b32_e64 v0, 0, 1, s[80:81]
	v_cmp_ne_u32_e64 s[46:47], 1, v0
	s_andn2_b64 vcc, exec, s[80:81]
	s_mov_b64 s[0:1], -1
	s_cbranch_vccnz .LBB0_903
	s_and_saveexec_b64 s[0:1], s[42:43]
	s_cbranch_execz .LBB0_902
	v_lshlrev_b64 v[116:117], 5, v[114:115]
	v_lshl_add_u64 v[116:117], s[52:53], 0, v[116:117]
	v_pk_mul_f32 v[120:121], v[110:111], v[118:119] op_sel_hi:[1,0]
	v_pk_mul_f32 v[122:123], v[112:113], v[118:119] op_sel_hi:[1,0]
	global_store_dwordx4 v[116:117], v[120:123], off
	s_nop 1
	v_pk_mul_f32 v[120:121], v[106:107], v[118:119] op_sel_hi:[1,0]
	v_pk_mul_f32 v[122:123], v[108:109], v[118:119] op_sel_hi:[1,0]
	global_store_dwordx4 v[116:117], v[120:123], off offset:16

; __device__ __forceinline__ unsigned pack2(float a, float b) { f32v2_t v = {a, b}; bf16v2_t r = __builtin_convertvector(v, bf16v2_t); return __builtin_bit_cast(unsigned, r); }
; template <int EPI, int N, int K>
; __device__ __forceinline__ void gemm_phase(const KP& p, int l, const bfr* A, const bfr* Bt) {
;     ...
; #pragma unroll
;             for (int bj = 0; bj < 2; ++bj) {
;               int col = ecol + bj * HALF + wc * 32 + fq * 8;
;               float v[8];
; #pragma unroll
;               for (int n = 0; n < 2; ++n)
; #pragma unroll
;                 for (int jj = 0; jj < 2; ++jj) {
;                   f32v2_t t2 = f32v2_t{acc[ai][bj][m][n][2 * jj], acc[ai][bj][m][n][2 * jj + 1]} * r;
;                   v[n * 4 + 2 * jj] = t2.x; v[n * 4 + 2 * jj + 1] = t2.y;
;                 }
;               u32x4 pk; pk[0] = pack2(v[0], v[1]); pk[1] = pack2(v[2], v[3]); pk[2] = pack2(v[4], v[5]); pk[3] = pack2(v[6], v[7]);
;               *(u32x4*)(proj + (size_t)row * NIN + col) = pk;
;               if (cdst) { *(float4*)(cdst + col - 512) = make_float4(v[0], v[1], v[2], v[3]); *(float4*)(cdst + col - 512 + 4) = make_float4(v[4], v[5], v[6], v[7]); }
;               if (tdst) *(u32x4*)(tdst + col - 512) = pk;
;             }
.LBB0_920:
	v_mov_b64_e32 v[116:117], s[36:37]
	s_movk_i32 s0, 0x1c00
	v_mad_i64_i32 v[124:125], s[0:1], v114, s0, v[116:117]
	v_pk_mul_f32 v[114:115], v[110:111], v[118:119] op_sel_hi:[1,0]
	v_pk_mul_f32 v[116:117], v[112:113], v[118:119] op_sel_hi:[1,0]
	v_pk_mul_f32 v[110:111], v[106:107], v[118:119] op_sel_hi:[1,0]
	v_pk_mul_f32 v[112:113], v[108:109], v[118:119] op_sel_hi:[1,0]
	v_ashrrev_i32_e32 v135, 31, v134
	v_cmp_ne_u64_e32 vcc, 0, v[122:123]
	v_cvt_pk_bf16_f32 v106, v114, v115
	v_cvt_pk_bf16_f32 v107, v116, v117
	v_cvt_pk_bf16_f32 v108, v110, v111
	v_cvt_pk_bf16_f32 v109, v112, v113
	v_lshl_add_u64 v[124:125], v[134:135], 1, v[124:125]
	v_lshl_add_u64 v[122:123], v[134:135], 2, v[122:123]
	global_store_dwordx4 v[124:125], v[106:109], off
	s_and_saveexec_b64 s[0:1], vcc
	s_cbranch_execz .LBB0_922
	global_store_dwordx4 v[122:123], v[114:117], off offset:-2048
	global_store_dwordx4 v[122:123], v[110:113], off offset:-2032

; template <int EPI, int N, int K>
; __device__ __forceinline__ void gemm_phase(const KP& p, int l, const bfr* A, const bfr* Bt) {
;     ...
;           int row = erow + ai * HM + wr * 64 + m * 16 + fr;
;           float r = rs[row];
;           if (epn < 14) {
;             float* cdst = nullptr;
;             bfr* tdst = nullptr;
;             if (ecol >= 512 && ecol < 1536) {
;               { int cid, tl;
;                 if (row < SROW0) { int s = row / PROW, pos = row % PROW; cid = s * 65 + (pos >> 6); tl = (pos & 63) - 61; }
;                 else { int rr = row - SROW0; cid = 520 + (rr >> 6); tl = (rr & 63) - 61; }
;                 if (tl >= 0) tdst = (bfr*)(p.ws + OFF_TAILS) + ((size_t)cid * 3 + tl) * 1024; }
;               if (row < SROW0) { int s = row / PROW, tl = row % PROW - (PLEN - 3); if (tl >= 0 && tl < 3) cdst = p.out + O_CP + ((size_t)(l * 8 + s) * 3 + tl) * 1024; }
;               else { int s = (row - SROW0) >> 6, tl = ((row - SROW0) & 63) - 61; if (tl >= 0) cdst = p.out + O_CS + ((size_t)(l * 8 + s) * 3 + tl) * 1024; }
;             }
; #pragma unroll
;             for (int bj = 0; bj < 2; ++bj) {
;               int col = ecol + bj * HALF + wc * 32 + fq * 8;
;               float v[8];
; #pragma unroll
;               for (int n = 0; n < 2; ++n)
; #pragma unroll
;                 for (int jj = 0; jj < 2; ++jj) {
;                   f32v2_t t2 = f32v2_t{acc[ai][bj][m][n][2 * jj], acc[ai][bj][m][n][2 * jj + 1]} * r;
;                   v[n * 4 + 2 * jj] = t2.x; v[n * 4 + 2 * jj + 1] = t2.y;
;                 }
;               u32x4 pk; pk[0] = pack2(v[0], v[1]); pk[1] = pack2(v[2], v[3]); pk[2] = pack2(v[4], v[5]); pk[3] = pack2(v[6], v[7]);
;               *(u32x4*)(proj + (size_t)row * NIN + col) = pk;
;               if (cdst) { *(float4*)(cdst + col - 512) = make_float4(v[0], v[1], v[2], v[3]); *(float4*)(cdst + col - 512 + 4) = make_float4(v[4], v[5], v[6], v[7]); }
;               if (tdst) *(u32x4*)(tdst + col - 512) = pk;
;             }
;           } else {
;             if (wc == 0 && fq == 0) {
;               *(float4*)(dtb + (size_t)row * 8) = make_float4(acc[ai][0][m][0][0] * r, acc[ai][0][m][0][1] * r, acc[ai][0][m][0][2] * r, acc[ai][0][m][0][3] * r);
;               *(float4*)(dtb + (size_t)row * 8 + 4) = make_float4(acc[ai][0][m][1][0] * r, acc[ai][0][m][1][1] * r, acc[ai][0][m][1][2] * r, acc[ai][0][m][1][3] * r);
.LBB0_929:
	s_nop 0
	v_add_u32_e32 v98, 32, v136
	v_ashrrev_i32_e32 v99, 31, v98
	v_lshl_add_u64 v[100:101], v[98:99], 2, s[50:51]
	v_mov_b32_e32 v102, v224
	s_and_b64 vcc, exec, s[46:47]
	s_mov_b64 s[0:1], -1
	s_cbranch_vccnz .LBB0_933
	s_and_saveexec_b64 s[0:1], s[42:43]
	s_cbranch_execz .LBB0_932
	v_lshlrev_b64 v[100:101], 5, v[98:99]
	v_lshl_add_u64 v[100:101], s[52:53], 0, v[100:101]
	v_pk_mul_f32 v[104:105], v[94:95], v[102:103] op_sel_hi:[1,0]
	v_pk_mul_f32 v[106:107], v[96:97], v[102:103] op_sel_hi:[1,0]
	global_store_dwordx4 v[100:101], v[104:107], off
	s_nop 1
	v_pk_mul_f32 v[104:105], v[90:91], v[102:103] op_sel_hi:[1,0]
	v_pk_mul_f32 v[106:107], v[92:93], v[102:103] op_sel_hi:[1,0]
	global_store_dwordx4 v[100:101], v[104:107], off offset:16

; __device__ __forceinline__ unsigned pack2(float a, float b) { f32v2_t v = {a, b}; bf16v2_t r = __builtin_convertvector(v, bf16v2_t); return __builtin_bit_cast(unsigned, r); }
; template <int EPI, int N, int K>
; __device__ __forceinline__ void gemm_phase(const KP& p, int l, const bfr* A, const bfr* Bt) {
;     ...
; #pragma unroll
;             for (int bj = 0; bj < 2; ++bj) {
;               int col = ecol + bj * HALF + wc * 32 + fq * 8;
;               float v[8];
; #pragma unroll
;               for (int n = 0; n < 2; ++n)
; #pragma unroll
;                 for (int jj = 0; jj < 2; ++jj) {
;                   f32v2_t t2 = f32v2_t{acc[ai][bj][m][n][2 * jj], acc[ai][bj][m][n][2 * jj + 1]} * r;
;                   v[n * 4 + 2 * jj] = t2.x; v[n * 4 + 2 * jj + 1] = t2.y;
;                 }
;               u32x4 pk; pk[0] = pack2(v[0], v[1]); pk[1] = pack2(v[2], v[3]); pk[2] = pack2(v[4], v[5]); pk[3] = pack2(v[6], v[7]);
;               *(u32x4*)(proj + (size_t)row * NIN + col) = pk;
;               if (cdst) { *(float4*)(cdst + col - 512) = make_float4(v[0], v[1], v[2], v[3]); *(float4*)(cdst + col - 512 + 4) = make_float4(v[4], v[5], v[6], v[7]); }
;               if (tdst) *(u32x4*)(tdst + col - 512) = pk;
;             }
.LBB0_950:
	v_mov_b64_e32 v[100:101], s[36:37]
	s_movk_i32 s0, 0x1c00
	v_mad_i64_i32 v[108:109], s[0:1], v98, s0, v[100:101]
	v_pk_mul_f32 v[98:99], v[94:95], v[102:103] op_sel_hi:[1,0]
	v_pk_mul_f32 v[100:101], v[96:97], v[102:103] op_sel_hi:[1,0]
	v_pk_mul_f32 v[94:95], v[90:91], v[102:103] op_sel_hi:[1,0]
	v_pk_mul_f32 v[96:97], v[92:93], v[102:103] op_sel_hi:[1,0]
	v_ashrrev_i32_e32 v135, 31, v134
	v_cmp_ne_u64_e32 vcc, 0, v[106:107]
	v_cvt_pk_bf16_f32 v90, v98, v99
	v_cvt_pk_bf16_f32 v91, v100, v101
	v_cvt_pk_bf16_f32 v92, v94, v95
	v_cvt_pk_bf16_f32 v93, v96, v97
	v_lshl_add_u64 v[108:109], v[134:135], 1, v[108:109]
	v_lshl_add_u64 v[106:107], v[134:135], 2, v[106:107]
	global_store_dwordx4 v[108:109], v[90:93], off
	s_and_saveexec_b64 s[0:1], vcc
	s_cbranch_execz .LBB0_952
	global_store_dwordx4 v[106:107], v[98:101], off offset:-2048
	global_store_dwordx4 v[106:107], v[94:97], off offset:-2032

; template <int EPI, int N, int K>
; __device__ __forceinline__ void gemm_phase(const KP& p, int l, const bfr* A, const bfr* Bt) {
;     ...
;           int row = erow + ai * HM + wr * 64 + m * 16 + fr;
;           float r = rs[row];
;           if (epn < 14) {
;             float* cdst = nullptr;
;             bfr* tdst = nullptr;
;             if (ecol >= 512 && ecol < 1536) {
;               { int cid, tl;
;                 if (row < SROW0) { int s = row / PROW, pos = row % PROW; cid = s * 65 + (pos >> 6); tl = (pos & 63) - 61; }
;                 else { int rr = row - SROW0; cid = 520 + (rr >> 6); tl = (rr & 63) - 61; }
;                 if (tl >= 0) tdst = (bfr*)(p.ws + OFF_TAILS) + ((size_t)cid * 3 + tl) * 1024; }
;               if (row < SROW0) { int s = row / PROW, tl = row % PROW - (PLEN - 3); if (tl >= 0 && tl < 3) cdst = p.out + O_CP + ((size_t)(l * 8 + s) * 3 + tl) * 1024; }
;               else { int s = (row - SROW0) >> 6, tl = ((row - SROW0) & 63) - 61; if (tl >= 0) cdst = p.out + O_CS + ((size_t)(l * 8 + s) * 3 + tl) * 1024; }
;             }
; #pragma unroll
;             for (int bj = 0; bj < 2; ++bj) {
;               int col = ecol + bj * HALF + wc * 32 + fq * 8;
;               float v[8];
; #pragma unroll
;               for (int n = 0; n < 2; ++n)
; #pragma unroll
;                 for (int jj = 0; jj < 2; ++jj) {
;                   f32v2_t t2 = f32v2_t{acc[ai][bj][m][n][2 * jj], acc[ai][bj][m][n][2 * jj + 1]} * r;
;                   v[n * 4 + 2 * jj] = t2.x; v[n * 4 + 2 * jj + 1] = t2.y;
;                 }
;               u32x4 pk; pk[0] = pack2(v[0], v[1]); pk[1] = pack2(v[2], v[3]); pk[2] = pack2(v[4], v[5]); pk[3] = pack2(v[6], v[7]);
;               *(u32x4*)(proj + (size_t)row * NIN + col) = pk;
;               if (cdst) { *(float4*)(cdst + col - 512) = make_float4(v[0], v[1], v[2], v[3]); *(float4*)(cdst + col - 512 + 4) = make_float4(v[4], v[5], v[6], v[7]); }
;               if (tdst) *(u32x4*)(tdst + col - 512) = pk;
;             }
;           } else {
;             if (wc == 0 && fq == 0) {
;               *(float4*)(dtb + (size_t)row * 8) = make_float4(acc[ai][0][m][0][0] * r, acc[ai][0][m][0][1] * r, acc[ai][0][m][0][2] * r, acc[ai][0][m][0][3] * r);
;               *(float4*)(dtb + (size_t)row * 8 + 4) = make_float4(acc[ai][0][m][1][0] * r, acc[ai][0][m][1][1] * r, acc[ai][0][m][1][2] * r, acc[ai][0][m][1][3] * r);
.LBB0_959:
	s_nop 0
	v_add_u32_e32 v82, 48, v136
	v_ashrrev_i32_e32 v83, 31, v82
	v_lshl_add_u64 v[84:85], v[82:83], 2, s[50:51]
	v_mov_b32_e32 v86, v225
	s_and_b64 vcc, exec, s[46:47]
	s_mov_b64 s[0:1], -1
	s_cbranch_vccnz .LBB0_963
	s_and_saveexec_b64 s[0:1], s[42:43]
	s_cbranch_execz .LBB0_962
	v_lshlrev_b64 v[84:85], 5, v[82:83]
	v_lshl_add_u64 v[84:85], s[52:53], 0, v[84:85]
	v_pk_mul_f32 v[88:89], v[78:79], v[86:87] op_sel_hi:[1,0]
	v_pk_mul_f32 v[90:91], v[80:81], v[86:87] op_sel_hi:[1,0]
	global_store_dwordx4 v[84:85], v[88:91], off
	s_nop 1
	v_pk_mul_f32 v[88:89], v[74:75], v[86:87] op_sel_hi:[1,0]
	v_pk_mul_f32 v[90:91], v[76:77], v[86:87] op_sel_hi:[1,0]
	global_store_dwordx4 v[84:85], v[88:91], off offset:16

; __device__ __forceinline__ unsigned pack2(float a, float b) { f32v2_t v = {a, b}; bf16v2_t r = __builtin_convertvector(v, bf16v2_t); return __builtin_bit_cast(unsigned, r); }
; template <int EPI, int N, int K>
; __device__ __forceinline__ void gemm_phase(const KP& p, int l, const bfr* A, const bfr* Bt) {
;     ...
; #pragma unroll
;             for (int bj = 0; bj < 2; ++bj) {
;               int col = ecol + bj * HALF + wc * 32 + fq * 8;
;               float v[8];
; #pragma unroll
;               for (int n = 0; n < 2; ++n)
; #pragma unroll
;                 for (int jj = 0; jj < 2; ++jj) {
;                   f32v2_t t2 = f32v2_t{acc[ai][bj][m][n][2 * jj], acc[ai][bj][m][n][2 * jj + 1]} * r;
;                   v[n * 4 + 2 * jj] = t2.x; v[n * 4 + 2 * jj + 1] = t2.y;
;                 }
;               u32x4 pk; pk[0] = pack2(v[0], v[1]); pk[1] = pack2(v[2], v[3]); pk[2] = pack2(v[4], v[5]); pk[3] = pack2(v[6], v[7]);
;               *(u32x4*)(proj + (size_t)row * NIN + col) = pk;
;               if (cdst) { *(float4*)(cdst + col - 512) = make_float4(v[0], v[1], v[2], v[3]); *(float4*)(cdst + col - 512 + 4) = make_float4(v[4], v[5], v[6], v[7]); }
;               if (tdst) *(u32x4*)(tdst + col - 512) = pk;
;             }
.LBB0_980:
	v_mov_b64_e32 v[84:85], s[36:37]
	s_movk_i32 s0, 0x1c00
	v_mad_i64_i32 v[92:93], s[0:1], v82, s0, v[84:85]
	v_pk_mul_f32 v[82:83], v[78:79], v[86:87] op_sel_hi:[1,0]
	v_pk_mul_f32 v[84:85], v[80:81], v[86:87] op_sel_hi:[1,0]
	v_pk_mul_f32 v[78:79], v[74:75], v[86:87] op_sel_hi:[1,0]
	v_pk_mul_f32 v[80:81], v[76:77], v[86:87] op_sel_hi:[1,0]
	v_ashrrev_i32_e32 v135, 31, v134
	v_cmp_ne_u64_e32 vcc, 0, v[90:91]
	v_cvt_pk_bf16_f32 v74, v82, v83
	v_cvt_pk_bf16_f32 v75, v84, v85
	v_cvt_pk_bf16_f32 v76, v78, v79
	v_cvt_pk_bf16_f32 v77, v80, v81
	v_lshl_add_u64 v[92:93], v[134:135], 1, v[92:93]
	v_lshl_add_u64 v[90:91], v[134:135], 2, v[90:91]
	global_store_dwordx4 v[92:93], v[74:77], off
	s_and_saveexec_b64 s[0:1], vcc
	s_cbranch_execz .LBB0_982
	global_store_dwordx4 v[90:91], v[82:85], off offset:-2048
	global_store_dwordx4 v[90:91], v[78:81], off offset:-2032

; template <int EPI, int N, int K>
; __device__ __forceinline__ void gemm_phase(const KP& p, int l, const bfr* A, const bfr* Bt) {
;     ...
;           int row = erow + ai * HM + wr * 64 + m * 16 + fr;
;           float r = rs[row];
;           if (epn < 14) {
;             float* cdst = nullptr;
;             bfr* tdst = nullptr;
;             if (ecol >= 512 && ecol < 1536) {
;               { int cid, tl;
;                 if (row < SROW0) { int s = row / PROW, pos = row % PROW; cid = s * 65 + (pos >> 6); tl = (pos & 63) - 61; }
;                 else { int rr = row - SROW0; cid = 520 + (rr >> 6); tl = (rr & 63) - 61; }
;                 if (tl >= 0) tdst = (bfr*)(p.ws + OFF_TAILS) + ((size_t)cid * 3 + tl) * 1024; }
;               if (row < SROW0) { int s = row / PROW, tl = row % PROW - (PLEN - 3); if (tl >= 0 && tl < 3) cdst = p.out + O_CP + ((size_t)(l * 8 + s) * 3 + tl) * 1024; }
;               else { int s = (row - SROW0) >> 6, tl = ((row - SROW0) & 63) - 61; if (tl >= 0) cdst = p.out + O_CS + ((size_t)(l * 8 + s) * 3 + tl) * 1024; }
;             }
; #pragma unroll
;             for (int bj = 0; bj < 2; ++bj) {
;               int col = ecol + bj * HALF + wc * 32 + fq * 8;
;               float v[8];
; #pragma unroll
;               for (int n = 0; n < 2; ++n)
; #pragma unroll
;                 for (int jj = 0; jj < 2; ++jj) {
;                   f32v2_t t2 = f32v2_t{acc[ai][bj][m][n][2 * jj], acc[ai][bj][m][n][2 * jj + 1]} * r;
;                   v[n * 4 + 2 * jj] = t2.x; v[n * 4 + 2 * jj + 1] = t2.y;
;                 }
;               u32x4 pk; pk[0] = pack2(v[0], v[1]); pk[1] = pack2(v[2], v[3]); pk[2] = pack2(v[4], v[5]); pk[3] = pack2(v[6], v[7]);
;               *(u32x4*)(proj + (size_t)row * NIN + col) = pk;
;               if (cdst) { *(float4*)(cdst + col - 512) = make_float4(v[0], v[1], v[2], v[3]); *(float4*)(cdst + col - 512 + 4) = make_float4(v[4], v[5], v[6], v[7]); }
;               if (tdst) *(u32x4*)(tdst + col - 512) = pk;
;             }
;           } else {
;             if (wc == 0 && fq == 0) {
;               *(float4*)(dtb + (size_t)row * 8) = make_float4(acc[ai][0][m][0][0] * r, acc[ai][0][m][0][1] * r, acc[ai][0][m][0][2] * r, acc[ai][0][m][0][3] * r);
;               *(float4*)(dtb + (size_t)row * 8 + 4) = make_float4(acc[ai][0][m][1][0] * r, acc[ai][0][m][1][1] * r, acc[ai][0][m][1][2] * r, acc[ai][0][m][1][3] * r);
.LBB0_989:
	s_nop 0
	v_add_u32_e32 v66, 0x80, v136
	v_ashrrev_i32_e32 v67, 31, v66
	v_lshl_add_u64 v[68:69], v[66:67], 2, s[50:51]
	v_mov_b32_e32 v70, v226
	s_and_b64 vcc, exec, s[46:47]
	s_mov_b64 s[0:1], -1
	s_cbranch_vccnz .LBB0_993
	s_and_saveexec_b64 s[0:1], s[42:43]
	s_cbranch_execz .LBB0_992
	v_lshlrev_b64 v[68:69], 5, v[66:67]
	v_lshl_add_u64 v[68:69], s[52:53], 0, v[68:69]
	v_pk_mul_f32 v[72:73], v[62:63], v[70:71] op_sel_hi:[1,0]
	v_pk_mul_f32 v[74:75], v[64:65], v[70:71] op_sel_hi:[1,0]
	global_store_dwordx4 v[68:69], v[72:75], off
	s_nop 1
	v_pk_mul_f32 v[72:73], v[58:59], v[70:71] op_sel_hi:[1,0]
	v_pk_mul_f32 v[74:75], v[60:61], v[70:71] op_sel_hi:[1,0]
	global_store_dwordx4 v[68:69], v[72:75], off offset:16

; __device__ __forceinline__ unsigned pack2(float a, float b) { f32v2_t v = {a, b}; bf16v2_t r = __builtin_convertvector(v, bf16v2_t); return __builtin_bit_cast(unsigned, r); }
; template <int EPI, int N, int K>
; __device__ __forceinline__ void gemm_phase(const KP& p, int l, const bfr* A, const bfr* Bt) {
;     ...
; #pragma unroll
;             for (int bj = 0; bj < 2; ++bj) {
;               int col = ecol + bj * HALF + wc * 32 + fq * 8;
;               float v[8];
; #pragma unroll
;               for (int n = 0; n < 2; ++n)
; #pragma unroll
;                 for (int jj = 0; jj < 2; ++jj) {
;                   f32v2_t t2 = f32v2_t{acc[ai][bj][m][n][2 * jj], acc[ai][bj][m][n][2 * jj + 1]} * r;
;                   v[n * 4 + 2 * jj] = t2.x; v[n * 4 + 2 * jj + 1] = t2.y;
;                 }
;               u32x4 pk; pk[0] = pack2(v[0], v[1]); pk[1] = pack2(v[2], v[3]); pk[2] = pack2(v[4], v[5]); pk[3] = pack2(v[6], v[7]);
;               *(u32x4*)(proj + (size_t)row * NIN + col) = pk;
;               if (cdst) { *(float4*)(cdst + col - 512) = make_float4(v[0], v[1], v[2], v[3]); *(float4*)(cdst + col - 512 + 4) = make_float4(v[4], v[5], v[6], v[7]); }
;               if (tdst) *(u32x4*)(tdst + col - 512) = pk;
;             }
.LBB0_1010:
	v_mov_b64_e32 v[68:69], s[36:37]
	s_movk_i32 s0, 0x1c00
	v_mad_i64_i32 v[76:77], s[0:1], v66, s0, v[68:69]
	v_pk_mul_f32 v[66:67], v[62:63], v[70:71] op_sel_hi:[1,0]
	v_pk_mul_f32 v[68:69], v[64:65], v[70:71] op_sel_hi:[1,0]
	v_pk_mul_f32 v[62:63], v[58:59], v[70:71] op_sel_hi:[1,0]
	v_pk_mul_f32 v[64:65], v[60:61], v[70:71] op_sel_hi:[1,0]
	v_ashrrev_i32_e32 v135, 31, v134
	v_cmp_ne_u64_e32 vcc, 0, v[74:75]
	v_cvt_pk_bf16_f32 v58, v66, v67
	v_cvt_pk_bf16_f32 v59, v68, v69
	v_cvt_pk_bf16_f32 v60, v62, v63
	v_cvt_pk_bf16_f32 v61, v64, v65
	v_lshl_add_u64 v[76:77], v[134:135], 1, v[76:77]
	v_lshl_add_u64 v[74:75], v[134:135], 2, v[74:75]
	global_store_dwordx4 v[76:77], v[58:61], off
	s_and_saveexec_b64 s[0:1], vcc
	s_cbranch_execz .LBB0_1012
	global_store_dwordx4 v[74:75], v[66:69], off offset:-2048
	global_store_dwordx4 v[74:75], v[62:65], off offset:-2032

; template <int EPI, int N, int K>
; __device__ __forceinline__ void gemm_phase(const KP& p, int l, const bfr* A, const bfr* Bt) {
;     ...
;           int row = erow + ai * HM + wr * 64 + m * 16 + fr;
;           float r = rs[row];
;           if (epn < 14) {
;             float* cdst = nullptr;
;             bfr* tdst = nullptr;
;             if (ecol >= 512 && ecol < 1536) {
;               { int cid, tl;
;                 if (row < SROW0) { int s = row / PROW, pos = row % PROW; cid = s * 65 + (pos >> 6); tl = (pos & 63) - 61; }
;                 else { int rr = row - SROW0; cid = 520 + (rr >> 6); tl = (rr & 63) - 61; }
;                 if (tl >= 0) tdst = (bfr*)(p.ws + OFF_TAILS) + ((size_t)cid * 3 + tl) * 1024; }
;               if (row < SROW0) { int s = row / PROW, tl = row % PROW - (PLEN - 3); if (tl >= 0 && tl < 3) cdst = p.out + O_CP + ((size_t)(l * 8 + s) * 3 + tl) * 1024; }
;               else { int s = (row - SROW0) >> 6, tl = ((row - SROW0) & 63) - 61; if (tl >= 0) cdst = p.out + O_CS + ((size_t)(l * 8 + s) * 3 + tl) * 1024; }
;             }
; #pragma unroll
;             for (int bj = 0; bj < 2; ++bj) {
;               int col = ecol + bj * HALF + wc * 32 + fq * 8;
;               float v[8];
; #pragma unroll
;               for (int n = 0; n < 2; ++n)
; #pragma unroll
;                 for (int jj = 0; jj < 2; ++jj) {
;                   f32v2_t t2 = f32v2_t{acc[ai][bj][m][n][2 * jj], acc[ai][bj][m][n][2 * jj + 1]} * r;
;                   v[n * 4 + 2 * jj] = t2.x; v[n * 4 + 2 * jj + 1] = t2.y;
;                 }
;               u32x4 pk; pk[0] = pack2(v[0], v[1]); pk[1] = pack2(v[2], v[3]); pk[2] = pack2(v[4], v[5]); pk[3] = pack2(v[6], v[7]);
;               *(u32x4*)(proj + (size_t)row * NIN + col) = pk;
;               if (cdst) { *(float4*)(cdst + col - 512) = make_float4(v[0], v[1], v[2], v[3]); *(float4*)(cdst + col - 512 + 4) = make_float4(v[4], v[5], v[6], v[7]); }
;               if (tdst) *(u32x4*)(tdst + col - 512) = pk;
;             }
;           } else {
;             if (wc == 0 && fq == 0) {
;               *(float4*)(dtb + (size_t)row * 8) = make_float4(acc[ai][0][m][0][0] * r, acc[ai][0][m][0][1] * r, acc[ai][0][m][0][2] * r, acc[ai][0][m][0][3] * r);
;               *(float4*)(dtb + (size_t)row * 8 + 4) = make_float4(acc[ai][0][m][1][0] * r, acc[ai][0][m][1][1] * r, acc[ai][0][m][1][2] * r, acc[ai][0][m][1][3] * r);
.LBB0_1019:
	s_nop 0
	v_add_u32_e32 v50, 0x90, v136
	v_ashrrev_i32_e32 v51, 31, v50
	v_lshl_add_u64 v[52:53], v[50:51], 2, s[50:51]
	v_mov_b32_e32 v54, v227
	s_and_b64 vcc, exec, s[46:47]
	s_mov_b64 s[0:1], -1
	s_cbranch_vccnz .LBB0_1023
	s_and_saveexec_b64 s[0:1], s[42:43]
	s_cbranch_execz .LBB0_1022
	v_lshlrev_b64 v[52:53], 5, v[50:51]
	v_lshl_add_u64 v[52:53], s[52:53], 0, v[52:53]
	v_pk_mul_f32 v[56:57], v[46:47], v[54:55] op_sel_hi:[1,0]
	v_pk_mul_f32 v[58:59], v[48:49], v[54:55] op_sel_hi:[1,0]
	global_store_dwordx4 v[52:53], v[56:59], off
	s_nop 1
	v_pk_mul_f32 v[56:57], v[42:43], v[54:55] op_sel_hi:[1,0]
	v_pk_mul_f32 v[58:59], v[44:45], v[54:55] op_sel_hi:[1,0]
	global_store_dwordx4 v[52:53], v[56:59], off offset:16

; __device__ __forceinline__ unsigned pack2(float a, float b) { f32v2_t v = {a, b}; bf16v2_t r = __builtin_convertvector(v, bf16v2_t); return __builtin_bit_cast(unsigned, r); }
; template <int EPI, int N, int K>
; __device__ __forceinline__ void gemm_phase(const KP& p, int l, const bfr* A, const bfr* Bt) {
;     ...
; #pragma unroll
;             for (int bj = 0; bj < 2; ++bj) {
;               int col = ecol + bj * HALF + wc * 32 + fq * 8;
;               float v[8];
; #pragma unroll
;               for (int n = 0; n < 2; ++n)
; #pragma unroll
;                 for (int jj = 0; jj < 2; ++jj) {
;                   f32v2_t t2 = f32v2_t{acc[ai][bj][m][n][2 * jj], acc[ai][bj][m][n][2 * jj + 1]} * r;
;                   v[n * 4 + 2 * jj] = t2.x; v[n * 4 + 2 * jj + 1] = t2.y;
;                 }
;               u32x4 pk; pk[0] = pack2(v[0], v[1]); pk[1] = pack2(v[2], v[3]); pk[2] = pack2(v[4], v[5]); pk[3] = pack2(v[6], v[7]);
;               *(u32x4*)(proj + (size_t)row * NIN + col) = pk;
;               if (cdst) { *(float4*)(cdst + col - 512) = make_float4(v[0], v[1], v[2], v[3]); *(float4*)(cdst + col - 512 + 4) = make_float4(v[4], v[5], v[6], v[7]); }
;               if (tdst) *(u32x4*)(tdst + col - 512) = pk;
;             }
.LBB0_1040:
	v_mov_b64_e32 v[52:53], s[36:37]
	s_movk_i32 s0, 0x1c00
	v_mad_i64_i32 v[60:61], s[0:1], v50, s0, v[52:53]
	v_pk_mul_f32 v[50:51], v[46:47], v[54:55] op_sel_hi:[1,0]
	v_pk_mul_f32 v[52:53], v[48:49], v[54:55] op_sel_hi:[1,0]
	v_pk_mul_f32 v[46:47], v[42:43], v[54:55] op_sel_hi:[1,0]
	v_pk_mul_f32 v[48:49], v[44:45], v[54:55] op_sel_hi:[1,0]
	v_ashrrev_i32_e32 v135, 31, v134
	v_cmp_ne_u64_e32 vcc, 0, v[58:59]
	v_cvt_pk_bf16_f32 v42, v50, v51
	v_cvt_pk_bf16_f32 v43, v52, v53
	v_cvt_pk_bf16_f32 v44, v46, v47
	v_cvt_pk_bf16_f32 v45, v48, v49
	v_lshl_add_u64 v[60:61], v[134:135], 1, v[60:61]
	v_lshl_add_u64 v[58:59], v[134:135], 2, v[58:59]
	global_store_dwordx4 v[60:61], v[42:45], off
	s_and_saveexec_b64 s[0:1], vcc
	s_cbranch_execz .LBB0_1042
	global_store_dwordx4 v[58:59], v[50:53], off offset:-2048
	global_store_dwordx4 v[58:59], v[46:49], off offset:-2032

; template <int EPI, int N, int K>
; __device__ __forceinline__ void gemm_phase(const KP& p, int l, const bfr* A, const bfr* Bt) {
;     ...
;           int row = erow + ai * HM + wr * 64 + m * 16 + fr;
;           float r = rs[row];
;           if (epn < 14) {
;             float* cdst = nullptr;
;             bfr* tdst = nullptr;
;             if (ecol >= 512 && ecol < 1536) {
;               { int cid, tl;
;                 if (row < SROW0) { int s = row / PROW, pos = row % PROW; cid = s * 65 + (pos >> 6); tl = (pos & 63) - 61; }
;                 else { int rr = row - SROW0; cid = 520 + (rr >> 6); tl = (rr & 63) - 61; }
;                 if (tl >= 0) tdst = (bfr*)(p.ws + OFF_TAILS) + ((size_t)cid * 3 + tl) * 1024; }
;               if (row < SROW0) { int s = row / PROW, tl = row % PROW - (PLEN - 3); if (tl >= 0 && tl < 3) cdst = p.out + O_CP + ((size_t)(l * 8 + s) * 3 + tl) * 1024; }
;               else { int s = (row - SROW0) >> 6, tl = ((row - SROW0) & 63) - 61; if (tl >= 0) cdst = p.out + O_CS + ((size_t)(l * 8 + s) * 3 + tl) * 1024; }
;             }
; #pragma unroll
;             for (int bj = 0; bj < 2; ++bj) {
;               int col = ecol + bj * HALF + wc * 32 + fq * 8;
;               float v[8];
; #pragma unroll
;               for (int n = 0; n < 2; ++n)
; #pragma unroll
;                 for (int jj = 0; jj < 2; ++jj) {
;                   f32v2_t t2 = f32v2_t{acc[ai][bj][m][n][2 * jj], acc[ai][bj][m][n][2 * jj + 1]} * r;
;                   v[n * 4 + 2 * jj] = t2.x; v[n * 4 + 2 * jj + 1] = t2.y;
;                 }
;               u32x4 pk; pk[0] = pack2(v[0], v[1]); pk[1] = pack2(v[2], v[3]); pk[2] = pack2(v[4], v[5]); pk[3] = pack2(v[6], v[7]);
;               *(u32x4*)(proj + (size_t)row * NIN + col) = pk;
;               if (cdst) { *(float4*)(cdst + col - 512) = make_float4(v[0], v[1], v[2], v[3]); *(float4*)(cdst + col - 512 + 4) = make_float4(v[4], v[5], v[6], v[7]); }
;               if (tdst) *(u32x4*)(tdst + col - 512) = pk;
;             }
;           } else {
;             if (wc == 0 && fq == 0) {
;               *(float4*)(dtb + (size_t)row * 8) = make_float4(acc[ai][0][m][0][0] * r, acc[ai][0][m][0][1] * r, acc[ai][0][m][0][2] * r, acc[ai][0][m][0][3] * r);
;               *(float4*)(dtb + (size_t)row * 8 + 4) = make_float4(acc[ai][0][m][1][0] * r, acc[ai][0][m][1][1] * r, acc[ai][0][m][1][2] * r, acc[ai][0][m][1][3] * r);
.LBB0_1049:
	s_nop 0
	v_add_u32_e32 v34, 0xa0, v136
	v_ashrrev_i32_e32 v35, 31, v34
	v_lshl_add_u64 v[36:37], v[34:35], 2, s[50:51]
	v_mov_b32_e32 v38, v228
	s_and_b64 vcc, exec, s[46:47]
	s_mov_b64 s[0:1], -1
	s_cbranch_vccnz .LBB0_1053
	s_and_saveexec_b64 s[0:1], s[42:43]
	s_cbranch_execz .LBB0_1052
	v_lshlrev_b64 v[36:37], 5, v[34:35]
	v_lshl_add_u64 v[36:37], s[52:53], 0, v[36:37]
	v_pk_mul_f32 v[40:41], v[30:31], v[38:39] op_sel_hi:[1,0]
	v_pk_mul_f32 v[42:43], v[32:33], v[38:39] op_sel_hi:[1,0]
	global_store_dwordx4 v[36:37], v[40:43], off
	s_nop 1
	v_pk_mul_f32 v[40:41], v[26:27], v[38:39] op_sel_hi:[1,0]
	v_pk_mul_f32 v[42:43], v[28:29], v[38:39] op_sel_hi:[1,0]
	global_store_dwordx4 v[36:37], v[40:43], off offset:16

; __device__ __forceinline__ unsigned pack2(float a, float b) { f32v2_t v = {a, b}; bf16v2_t r = __builtin_convertvector(v, bf16v2_t); return __builtin_bit_cast(unsigned, r); }
; template <int EPI, int N, int K>
; __device__ __forceinline__ void gemm_phase(const KP& p, int l, const bfr* A, const bfr* Bt) {
;     ...
; #pragma unroll
;             for (int bj = 0; bj < 2; ++bj) {
;               int col = ecol + bj * HALF + wc * 32 + fq * 8;
;               float v[8];
; #pragma unroll
;               for (int n = 0; n < 2; ++n)
; #pragma unroll
;                 for (int jj = 0; jj < 2; ++jj) {
;                   f32v2_t t2 = f32v2_t{acc[ai][bj][m][n][2 * jj], acc[ai][bj][m][n][2 * jj + 1]} * r;
;                   v[n * 4 + 2 * jj] = t2.x; v[n * 4 + 2 * jj + 1] = t2.y;
;                 }
;               u32x4 pk; pk[0] = pack2(v[0], v[1]); pk[1] = pack2(v[2], v[3]); pk[2] = pack2(v[4], v[5]); pk[3] = pack2(v[6], v[7]);
;               *(u32x4*)(proj + (size_t)row * NIN + col) = pk;
;               if (cdst) { *(float4*)(cdst + col - 512) = make_float4(v[0], v[1], v[2], v[3]); *(float4*)(cdst + col - 512 + 4) = make_float4(v[4], v[5], v[6], v[7]); }
;               if (tdst) *(u32x4*)(tdst + col - 512) = pk;
;             }
.LBB0_1070:
	v_mov_b64_e32 v[36:37], s[36:37]
	s_movk_i32 s0, 0x1c00
	v_mad_i64_i32 v[44:45], s[0:1], v34, s0, v[36:37]
	v_pk_mul_f32 v[34:35], v[30:31], v[38:39] op_sel_hi:[1,0]
	v_pk_mul_f32 v[36:37], v[32:33], v[38:39] op_sel_hi:[1,0]
	v_pk_mul_f32 v[30:31], v[26:27], v[38:39] op_sel_hi:[1,0]
	v_pk_mul_f32 v[32:33], v[28:29], v[38:39] op_sel_hi:[1,0]
	v_ashrrev_i32_e32 v135, 31, v134
	v_cmp_ne_u64_e32 vcc, 0, v[42:43]
	v_cvt_pk_bf16_f32 v26, v34, v35
	v_cvt_pk_bf16_f32 v27, v36, v37
	v_cvt_pk_bf16_f32 v28, v30, v31
	v_cvt_pk_bf16_f32 v29, v32, v33
	v_lshl_add_u64 v[44:45], v[134:135], 1, v[44:45]
	v_lshl_add_u64 v[42:43], v[134:135], 2, v[42:43]
	global_store_dwordx4 v[44:45], v[26:29], off
	s_and_saveexec_b64 s[0:1], vcc
	s_cbranch_execz .LBB0_1072
	global_store_dwordx4 v[42:43], v[34:37], off offset:-2048
	global_store_dwordx4 v[42:43], v[30:33], off offset:-2032

; template <int EPI, int N, int K>
; __device__ __forceinline__ void gemm_phase(const KP& p, int l, const bfr* A, const bfr* Bt) {
;     ...
;           int row = erow + ai * HM + wr * 64 + m * 16 + fr;
;           float r = rs[row];
;           if (epn < 14) {
;             float* cdst = nullptr;
;             bfr* tdst = nullptr;
;             if (ecol >= 512 && ecol < 1536) {
;               { int cid, tl;
;                 if (row < SROW0) { int s = row / PROW, pos = row % PROW; cid = s * 65 + (pos >> 6); tl = (pos & 63) - 61; }
;                 else { int rr = row - SROW0; cid = 520 + (rr >> 6); tl = (rr & 63) - 61; }
;                 if (tl >= 0) tdst = (bfr*)(p.ws + OFF_TAILS) + ((size_t)cid * 3 + tl) * 1024; }
;               if (row < SROW0) { int s = row / PROW, tl = row % PROW - (PLEN - 3); if (tl >= 0 && tl < 3) cdst = p.out + O_CP + ((size_t)(l * 8 + s) * 3 + tl) * 1024; }
;               else { int s = (row - SROW0) >> 6, tl = ((row - SROW0) & 63) - 61; if (tl >= 0) cdst = p.out + O_CS + ((size_t)(l * 8 + s) * 3 + tl) * 1024; }
;             }
; #pragma unroll
;             for (int bj = 0; bj < 2; ++bj) {
;               int col = ecol + bj * HALF + wc * 32 + fq * 8;
;               float v[8];
; #pragma unroll
;               for (int n = 0; n < 2; ++n)
; #pragma unroll
;                 for (int jj = 0; jj < 2; ++jj) {
;                   f32v2_t t2 = f32v2_t{acc[ai][bj][m][n][2 * jj], acc[ai][bj][m][n][2 * jj + 1]} * r;
;                   v[n * 4 + 2 * jj] = t2.x; v[n * 4 + 2 * jj + 1] = t2.y;
;                 }
;               u32x4 pk; pk[0] = pack2(v[0], v[1]); pk[1] = pack2(v[2], v[3]); pk[2] = pack2(v[4], v[5]); pk[3] = pack2(v[6], v[7]);
;               *(u32x4*)(proj + (size_t)row * NIN + col) = pk;
;               if (cdst) { *(float4*)(cdst + col - 512) = make_float4(v[0], v[1], v[2], v[3]); *(float4*)(cdst + col - 512 + 4) = make_float4(v[4], v[5], v[6], v[7]); }
;               if (tdst) *(u32x4*)(tdst + col - 512) = pk;
;             }
;           } else {
;             if (wc == 0 && fq == 0) {
;               *(float4*)(dtb + (size_t)row * 8) = make_float4(acc[ai][0][m][0][0] * r, acc[ai][0][m][0][1] * r, acc[ai][0][m][0][2] * r, acc[ai][0][m][0][3] * r);
;               *(float4*)(dtb + (size_t)row * 8 + 4) = make_float4(acc[ai][0][m][1][0] * r, acc[ai][0][m][1][1] * r, acc[ai][0][m][1][2] * r, acc[ai][0][m][1][3] * r);
.LBB0_1079:
	s_nop 0
	v_add_u32_e32 v18, 0xb0, v136
	v_ashrrev_i32_e32 v19, 31, v18
	v_lshl_add_u64 v[20:21], v[18:19], 2, s[50:51]
	v_mov_b32_e32 v22, v229
	s_and_b64 vcc, exec, s[46:47]
	s_mov_b64 s[0:1], -1
	s_cbranch_vccnz .LBB0_1083
	s_and_saveexec_b64 s[0:1], s[42:43]
	s_cbranch_execz .LBB0_1082
	v_lshlrev_b64 v[20:21], 5, v[18:19]
	v_lshl_add_u64 v[20:21], s[52:53], 0, v[20:21]
	v_pk_mul_f32 v[24:25], v[14:15], v[22:23] op_sel_hi:[1,0]
	v_pk_mul_f32 v[26:27], v[16:17], v[22:23] op_sel_hi:[1,0]
	global_store_dwordx4 v[20:21], v[24:27], off
	s_nop 1
	v_pk_mul_f32 v[24:25], v[10:11], v[22:23] op_sel_hi:[1,0]
	v_pk_mul_f32 v[26:27], v[12:13], v[22:23] op_sel_hi:[1,0]
	global_store_dwordx4 v[20:21], v[24:27], off offset:16

; __device__ __forceinline__ unsigned pack2(float a, float b) { f32v2_t v = {a, b}; bf16v2_t r = __builtin_convertvector(v, bf16v2_t); return __builtin_bit_cast(unsigned, r); }
; template <int EPI, int N, int K>
; __device__ __forceinline__ void gemm_phase(const KP& p, int l, const bfr* A, const bfr* Bt) {
;     ...
; #pragma unroll
;             for (int bj = 0; bj < 2; ++bj) {
;               int col = ecol + bj * HALF + wc * 32 + fq * 8;
;               float v[8];
; #pragma unroll
;               for (int n = 0; n < 2; ++n)
; #pragma unroll
;                 for (int jj = 0; jj < 2; ++jj) {
;                   f32v2_t t2 = f32v2_t{acc[ai][bj][m][n][2 * jj], acc[ai][bj][m][n][2 * jj + 1]} * r;
;                   v[n * 4 + 2 * jj] = t2.x; v[n * 4 + 2 * jj + 1] = t2.y;
;                 }
;               u32x4 pk; pk[0] = pack2(v[0], v[1]); pk[1] = pack2(v[2], v[3]); pk[2] = pack2(v[4], v[5]); pk[3] = pack2(v[6], v[7]);
;               *(u32x4*)(proj + (size_t)row * NIN + col) = pk;
;               if (cdst) { *(float4*)(cdst + col - 512) = make_float4(v[0], v[1], v[2], v[3]); *(float4*)(cdst + col - 512 + 4) = make_float4(v[4], v[5], v[6], v[7]); }
;               if (tdst) *(u32x4*)(tdst + col - 512) = pk;
;             }
.LBB0_1100:
	v_mov_b64_e32 v[20:21], s[36:37]
	s_movk_i32 s0, 0x1c00
	v_mad_i64_i32 v[28:29], s[0:1], v18, s0, v[20:21]
	v_pk_mul_f32 v[18:19], v[14:15], v[22:23] op_sel_hi:[1,0]
	v_pk_mul_f32 v[20:21], v[16:17], v[22:23] op_sel_hi:[1,0]
	v_pk_mul_f32 v[14:15], v[10:11], v[22:23] op_sel_hi:[1,0]
	v_pk_mul_f32 v[16:17], v[12:13], v[22:23] op_sel_hi:[1,0]
	v_ashrrev_i32_e32 v135, 31, v134
	v_cmp_ne_u64_e32 vcc, 0, v[26:27]
	v_cvt_pk_bf16_f32 v10, v18, v19
	v_cvt_pk_bf16_f32 v11, v20, v21
	v_cvt_pk_bf16_f32 v12, v14, v15
	v_cvt_pk_bf16_f32 v13, v16, v17
	v_lshl_add_u64 v[28:29], v[134:135], 1, v[28:29]
	v_lshl_add_u64 v[26:27], v[134:135], 2, v[26:27]
	global_store_dwordx4 v[28:29], v[10:13], off
	s_and_saveexec_b64 s[0:1], vcc
	s_cbranch_execz .LBB0_1102
	global_store_dwordx4 v[26:27], v[18:21], off offset:-2048
	global_store_dwordx4 v[26:27], v[14:17], off offset:-2032

; #define STAGE_A(P, BASE, br, kt) STAGE_B(P, BASE, br, kt)
; template <int EPI, int N, int K>
; __device__ __forceinline__ void gemm_phase(const KP& p, int l, const bfr* A, const bfr* Bt) {
;     ...
;     if (Lt + p.nblk < nwg) {
;       TILE_COORDS(Lt + p.nblk, brow, bcol, pn);
;       STAGE_B(SB(0, 0), Bt, bcol, 0); STAGE_A(SA(0, 0), A, brow, 0);
;       STAGE_B(SB(0, 1), Bt, bcol + HALF, 0); STAGE_A(SA(0, 1), A, brow + HM, 0);
;     }
;     ...
;               *(u32x4*)(proj + (size_t)row * NIN + col) = pk;
;               if (cdst) { *(float4*)(cdst + col - 512) = make_float4(v[0], v[1], v[2], v[3]); *(float4*)(cdst + col - 512 + 4) = make_float4(v[4], v[5], v[6], v[7]); }
;               if (tdst) *(u32x4*)(tdst + col - 512) = pk;
;             }
.LBB0_1106:
	s_or_b64 exec, exec, s[44:45]
	s_and_saveexec_b64 s[44:45], s[0:1]
	s_cbranch_execz .LBB0_855
	global_store_dwordx4 v[14:15], v[2:5], off offset:-768
	s_branch .LBB0_855
.Lepi3_nonext:
	global_load_dword v232, v[230:231], off
	global_load_dword v232, v[230:231], off
	global_load_dword v232, v[230:231], off
	global_load_dword v232, v[230:231], off
	global_load_dword v232, v[230:231], off
	global_load_dword v232, v[230:231], off
	global_load_dword v232, v[230:231], off
	global_load_dword v232, v[230:231], off
	s_branch .LBB0_869
.LBB0_1108:
	s_mov_b64 s[88:89], -1
	s_mov_b32 s67, 16
	s_mov_b32 s95, 0
	s_mov_b32 s33, 0

; #define STAGE_A(P, BASE, br, kt) STAGE_B(P, BASE, br, kt)
; template <int EPI, int N, int K>
; __device__ __forceinline__ void gemm_phase(const KP& p, int l, const bfr* A, const bfr* Bt) {
;     ...
;   int tid = threadIdx.x; asm volatile("" : "+v"(tid));
;   const int wid = tid >> 6, lane = tid & 63, wr = wid >> 2, wc = wid & 3, fr = lane & 15, fq = lane >> 4;
;   const int nt = K / BK;
;   unsigned so0, so1;
;   { int _r, _c; stage_rc(tid * 16, _r, _c); so0 = (unsigned)(_r * K + _c) * 2u; stage_rc(tid * 16 + 8192, _r, _c); so1 = (unsigned)(_r * K + _c) * 2u; }
;     ...
;   int brow = 0, bcol = 0, pn = 0;
;   if (p.bid < nwg) {
;     TILE_COORDS(p.bid, brow, bcol, pn);
;     STAGE_B(SB(0, 0), Bt, bcol, 0); STAGE_A(SA(0, 0), A, brow, 0);
;     STAGE_B(SB(0, 1), Bt, bcol + HALF, 0); STAGE_A(SA(0, 1), A, brow + HM, 0);
;   }
.LBB0_1138:
	s_and_b64 vcc, exec, s[44:45]
	s_cbranch_vccz .LBB0_1150
	v_readlane_b32 s0, v255, 42
	v_mov_b32_e32 v0, v156
	s_cmpk_gt_i32 s0, 0xb57
	v_readlane_b32 s33, v255, 41
	s_cbranch_scc1 .LBB0_1151
	s_waitcnt vmcnt(0)
	v_bfe_i32 v3, v0, 27, 1
	v_lshlrev_b32_e32 v136, 4, v0
	v_lshrrev_b32_e32 v3, 22, v3
	v_add_u32_e32 v3, v136, v3
	v_and_b32_e32 v3, 0xfffffc00, v3
	v_sub_u32_e32 v3, v136, v3
	v_lshrrev_b32_e32 v4, 4, v3
	v_bitop3_b32 v3, v4, v3, 32 bitop3:0x6c
	v_ashrrev_i32_e32 v2, 31, v0
	v_ashrrev_i32_e32 v5, 31, v3
	v_lshrrev_b32_e32 v2, 26, v2
	v_lshrrev_b32_e32 v5, 26, v5
	v_add_u32_e32 v2, v0, v2
	v_add_u32_e32 v5, v3, v5
	v_ashrrev_i32_e32 v2, 6, v2
	v_lshrrev_b32_e32 v6, 6, v5
	v_and_b32_e32 v5, 0xc0, v5
	v_lshlrev_b32_e32 v4, 3, v2
	v_lshlrev_b32_e32 v2, 5, v2
	v_sub_u32_e32 v3, v3, v5
	v_and_b32_e32 v4, 0x1ffff0, v4
	v_and_b32_e32 v2, 32, v2
	v_ashrrev_i16_sdwa v3, v163, sext(v3) dst_sel:DWORD dst_unused:UNUSED_PAD src0_sel:DWORD src1_sel:BYTE_0
	v_readlane_b32 s16, v255, 42
	v_add_u32_sdwa v2, v2, sext(v3) dst_sel:DWORD dst_unused:UNUSED_PAD src0_sel:DWORD src1_sel:WORD_0
	v_add_lshl_u32 v3, v6, v4, 11
	s_ashr_i32 s0, s16, 31
	v_lshl_add_u32 v137, v2, 1, v3
	v_add_u32_e32 v2, 0x2000, v136
	s_lshr_b32 s0, s0, 29
	v_ashrrev_i32_e32 v3, 31, v2
	s_add_i32 s0, s16, s0
	v_lshrrev_b32_e32 v3, 22, v3
	s_ashr_i32 s1, s0, 3
	s_and_b32 s0, s0, -8
	v_add_u32_e32 v3, v2, v3
	s_sub_i32 s0, s16, s0
	v_ashrrev_i32_e32 v3, 10, v3
	s_cmp_lt_i32 s0, 0
	s_movk_i32 s2, 0x16c
	v_mul_i32_i24_e32 v4, 0x400, v3
	s_cselect_b32 s2, s2, 0x16b
	v_sub_u32_e32 v2, v2, v4
	s_mul_i32 s0, s2, s0
	v_lshrrev_b32_e32 v4, 4, v2
	s_add_i32 s0, s0, s1
	v_bitop3_b32 v2, v4, v2, 32 bitop3:0x6c
	s_mul_hi_i32 s1, s0, 0x2e8ba2e9
	v_ashrrev_i32_e32 v5, 31, v2
	s_lshr_b32 s2, s1, 31
	s_ashr_i32 s1, s1, 5
	v_lshrrev_b32_e32 v5, 26, v5
	s_add_i32 s1, s1, s2
	v_add_u32_e32 v5, v2, v5
	s_lshl_b32 s2, s1, 3
	v_lshrrev_b32_e32 v6, 6, v5
	v_and_b32_e32 v5, 0xc0, v5
	s_sub_i32 s3, 0x84, s2
	v_lshlrev_b32_e32 v4, 3, v3
	v_lshlrev_b32_e32 v3, 5, v3
	v_sub_u32_e32 v2, v2, v5
	s_min_u32 s3, s3, 8
	s_mulk_i32 s1, 0xb0
	v_and_b32_e32 v4, 0x1ffff0, v4
	v_and_b32_e32 v3, 32, v3
	v_ashrrev_i16_sdwa v2, v163, sext(v2) dst_sel:DWORD dst_unused:UNUSED_PAD src0_sel:DWORD src1_sel:BYTE_0
	s_sub_i32 s14, s0, s1
	v_cvt_f32_ubyte0_e32 v5, s3
	v_add_u32_sdwa v2, v3, sext(v2) dst_sel:DWORD dst_unused:UNUSED_PAD src0_sel:DWORD src1_sel:WORD_0
	v_add_lshl_u32 v3, v6, v4, 11
	v_cvt_f32_i32_e32 v4, s14
	v_rcp_iflag_f32_e32 v6, v5
	v_lshl_add_u32 v138, v2, 1, v3
	s_ashr_i32 s0, s14, 30
	s_or_b32 s15, s0, 1
	v_mul_f32_e32 v2, v4, v6
	v_trunc_f32_e32 v2, v2
	v_fma_f32 v3, -v2, v5, v4
	v_cvt_i32_f32_e32 v2, v2
	v_cmp_ge_f32_e64 s[0:1], |v3|, v5
	s_and_b64 s[0:1], s[0:1], exec
	s_cselect_b32 s0, s15, 0
	v_readfirstlane_b32 s1, v2
	s_add_i32 s0, s1, s0
	s_sext_i32_i16 s1, s0
	s_mul_i32 s0, s0, s3
	s_sub_i32 s0, s14, s0
	s_sext_i32_i16 s0, s0
	s_lshl_b32 s50, s1, 8
	s_add_i32 s2, s2, s0
	s_ashr_i32 s51, s50, 31
	s_lshl_b32 s46, s2, 8
	s_lshl_b64 s[0:1], s[50:51], 11
	v_readlane_b32 s3, v255, 57
	v_add_u32_e32 v139, s33, v136
	s_add_u32 s0, s3, s0
	v_readlane_b32 s17, v255, 58
	v_readfirstlane_b32 s2, v139
	v_add_u32_e32 v140, 0x2000, v139
	s_addc_u32 s1, s17, s1
	v_mov_b32_e32 v2, v137
	v_mov_b32_e32 v3, v138
	s_mov_b32 m0, s2
	v_readfirstlane_b32 s2, v140
	s_ashr_i32 s47, s46, 31
	global_load_lds_dwordx4 v2, s[0:1]
	s_mov_b32 m0, s2
	v_readlane_b32 s14, v255, 45
	global_load_lds_dwordx4 v3, s[0:1]
	s_lshl_b64 s[0:1], s[46:47], 11
	v_add_u32_e32 v141, 0, v136
	v_readlane_b32 s15, v255, 46
	s_add_u32 s0, s14, s0
	v_readfirstlane_b32 s2, v141
	v_add_u32_e32 v142, 0x2000, v141
	s_addc_u32 s1, s15, s1
	v_mov_b32_e32 v2, v137
	v_mov_b32_e32 v3, v138
	s_mov_b32 m0, s2
	v_readfirstlane_b32 s2, v142
	v_add_u32_e32 v143, s66, v136
	global_load_lds_dwordx4 v2, s[0:1]
	s_mov_b32 m0, s2
	v_readfirstlane_b32 s2, v143
	global_load_lds_dwordx4 v3, s[0:1]
	s_or_b32 s0, s50, 0x80
	s_ashr_i32 s1, s0, 31
	s_lshl_b64 s[0:1], s[0:1], 11
	s_add_u32 s0, s3, s0
	v_add_u32_e32 v144, 0x2000, v143
	s_addc_u32 s1, s17, s1
	v_mov_b32_e32 v2, v137
	v_mov_b32_e32 v3, v138
	s_mov_b32 m0, s2
	v_readfirstlane_b32 s2, v144
	v_add_u32_e32 v145, 0x4000, v141
	global_load_lds_dwordx4 v2, s[0:1]
	s_mov_b32 m0, s2
	v_readfirstlane_b32 s2, v145
	global_load_lds_dwordx4 v3, s[0:1]
	s_or_b32 s0, s46, 0x80
	s_ashr_i32 s1, s0, 31
	s_lshl_b64 s[0:1], s[0:1], 11
	s_add_u32 s0, s14, s0
	v_add_u32_e32 v146, 0x6000, v141
	s_addc_u32 s1, s15, s1
	v_mov_b32_e32 v2, v137
	v_mov_b32_e32 v3, v138
	s_mov_b32 m0, s2
	v_readfirstlane_b32 s2, v146
	s_waitcnt lgkmcnt(0)
	v_lshlrev_b32_e32 v8, 2, v0
	global_load_lds_dwordx4 v2, s[0:1]
	s_mov_b32 m0, s2
	v_and_b32_e32 v2, 48, v0
	global_load_lds_dwordx4 v3, s[0:1]
	v_and_b32_e32 v3, 15, v0
	v_lshlrev_b32_e32 v7, 6, v3
	v_and_b32_e32 v8, 32, v8
	v_bitop3_b32 v7, v2, v8, v7 bitop3:0x36
	v_readlane_b32 s0, v254, 48
	v_bfe_u32 v4, v0, 6, 2
	v_ashrrev_i32_e32 v5, 8, v0
	v_add_u32_e32 v11, s0, v7
	v_readlane_b32 s0, v254, 49
	v_lshlrev_b32_e32 v13, 13, v5
	v_cmp_eq_u32_e64 s[38:39], 1, v5
	v_add_u32_e32 v12, s0, v7
	s_movk_i32 s0, 0x100
	v_cmp_gt_u32_e64 s[40:41], s0, v0
	v_lshlrev_b32_e32 v0, 6, v0
	s_movk_i32 s0, 0x3c0
	v_and_or_b32 v0, v0, s0, v2
	v_xad_u32 v8, v0, v8, 0
	v_lshlrev_b32_e32 v0, 6, v4
	v_lshlrev_b32_e32 v6, 12, v4
	v_add_u32_e32 v9, s33, v7
	v_add_u32_e32 v10, s66, v7
	v_lshl_or_b32 v147, v5, 6, v3
	v_add_u32_e32 v7, 0, v7
	v_or_b32_e32 v14, 0x800, v13
	v_or_b32_e32 v15, 0x1000, v13
	v_or_b32_e32 v16, 0x1800, v13
	v_lshl_add_u64 v[4:5], s[36:37], 0, v[0:1]
	v_mov_b32_e32 v3, v1
	s_add_u32 s0, s14, 0x4200000
	v_lshl_add_u64 v[130:131], v[4:5], 0, v[2:3]
	s_addc_u32 s1, s15, 0
	v_add_u32_e32 v148, v9, v6
	v_add_u32_e32 v149, v7, v13
	v_add_u32_e32 v150, v8, v14
	v_add_u32_e32 v151, v8, v15
	v_add_u32_e32 v152, v8, v16
	v_add_u32_e32 v153, v10, v6
	v_add_u32_e32 v154, v11, v6
	v_add_u32_e32 v155, v12, v6
	s_mov_b32 s33, s16
	global_load_dword v253, v[130:131], off
	global_load_dword v253, v[130:131], off
	global_load_dword v253, v[130:131], off
	global_load_dword v253, v[130:131], off
	global_load_dword v253, v[130:131], off
	global_load_dword v253, v[130:131], off
	global_load_dword v253, v[130:131], off
	global_load_dword v253, v[130:131], off
	s_branch .LBB0_1142

; #define STAGE_A(P, BASE, br, kt) STAGE_B(P, BASE, br, kt)
; #define WAIT_V(n) asm volatile("s_waitcnt vmcnt(" #n ")" ::: "memory")
; #define BAR __builtin_amdgcn_s_barrier()
; template <int EPI, int N, int K>
; __device__ __forceinline__ void gemm_phase(const KP& p, int l, const bfr* A, const bfr* Bt) {
;     ...
;   for (int Lt = p.bid; Lt < nwg; Lt += p.nblk) {
;     f32x4 acc[2][2][4][2];
; #pragma unroll
;     for (int a = 0; a < 2; ++a)
; #pragma unroll
;       for (int b = 0; b < 2; ++b)
; #pragma unroll
;         for (int m = 0; m < 4; ++m)
; #pragma unroll
;           for (int n = 0; n < 2; ++n) acc[a][b][m][n] = f32x4{0.f, 0.f, 0.f, 0.f};
;     bf16x8 At[4][2], B0[2][2], B1[2][2];
;     if (wr == 1) BAR;
;     WAIT_V(4); BAR;
;     STAGE_B(SB(1, 0), Bt, bcol, 1); STAGE_A(SA(1, 0), A, brow, 1); STAGE_B(SB(1, 1), Bt, bcol + HALF, 1);
;     WAIT_V(6); BAR;
.LBB0_1144:
	s_or_b64 exec, exec, s[36:37]
	s_ashr_i32 s51, s50, 31
	s_lshl_b64 s[2:3], s[50:51], 11
	v_readlane_b32 s18, v255, 57
	s_add_u32 s14, s18, s2
	v_readlane_b32 s19, v255, 58
	v_readlane_b32 s36, v254, 48
	s_addc_u32 s15, s19, s3
	v_mov_b32_e32 v2, v138
	v_mov_b32_e32 v0, v137
	v_add_u32_e32 v132, s36, v136
	s_waitcnt vmcnt(12)
	s_barrier
	s_mov_b64 s[44:45], 0x80
	v_lshl_add_u64 v[4:5], s[14:15], 0, v[0:1]
	v_readfirstlane_b32 s36, v132
	v_mov_b32_e32 v3, v1
	v_add_u32_e32 v133, 0x2000, v132
	s_ashr_i32 s47, s46, 31
	v_lshl_add_u64 v[4:5], v[4:5], 0, s[44:45]
	s_mov_b32 m0, s36
	v_lshl_add_u64 v[2:3], s[14:15], 0, v[2:3]
	v_readfirstlane_b32 s14, v133
	s_lshl_b64 s[36:37], s[46:47], 11
	v_readlane_b32 s16, v255, 45
	global_load_lds_dwordx4 v[4:5], off
	v_lshl_add_u64 v[2:3], v[2:3], 0, s[44:45]
	s_mov_b32 m0, s14
	v_readlane_b32 s17, v255, 46
	s_add_u32 s14, s16, s36
	global_load_lds_dwordx4 v[2:3], off
	s_addc_u32 s15, s17, s37
	v_mov_b32_e32 v2, v138
	v_mov_b32_e32 v0, v137
	v_add_u32_e32 v134, 0x8000, v141
	v_mov_b32_e32 v3, v1
	v_lshl_add_u64 v[4:5], s[14:15], 0, v[0:1]
	v_readfirstlane_b32 s42, v134
	v_add_u32_e32 v135, 0xa000, v141
	v_lshl_add_u64 v[4:5], v[4:5], 0, s[44:45]
	s_mov_b32 m0, s42
	v_lshl_add_u64 v[2:3], s[14:15], 0, v[2:3]
	v_readfirstlane_b32 s14, v135
	global_load_lds_dwordx4 v[4:5], off
	s_mov_b32 m0, s14
	s_or_b32 s14, s50, 0x80
	s_ashr_i32 s15, s14, 31
	s_lshl_b64 s[14:15], s[14:15], 11
	v_lshl_add_u64 v[2:3], v[2:3], 0, s[44:45]
	s_add_u32 s14, s18, s14
	v_readlane_b32 s42, v254, 49
	global_load_lds_dwordx4 v[2:3], off
	s_addc_u32 s15, s19, s15
	v_mov_b32_e32 v0, v137
	v_mov_b32_e32 v2, v138
	v_add_u32_e32 v174, s42, v136
	v_mov_b32_e32 v3, v1
	v_lshl_add_u64 v[4:5], s[14:15], 0, v[0:1]
	v_readfirstlane_b32 s42, v174
	v_add_u32_e32 v175, 0x2000, v174
	v_lshl_add_u64 v[4:5], v[4:5], 0, s[44:45]
	s_mov_b32 m0, s42
	v_lshl_add_u64 v[2:3], s[14:15], 0, v[2:3]
	v_readfirstlane_b32 s14, v175
	global_load_lds_dwordx4 v[4:5], off
	v_lshl_add_u64 v[2:3], v[2:3], 0, s[44:45]
	s_mov_b32 m0, s14
	v_readlane_b32 s14, v255, 55
	global_load_lds_dwordx4 v[2:3], off
	s_waitcnt vmcnt(14)
	s_add_u32 s2, s14, s2
	v_readlane_b32 s14, v255, 56
	v_mov_b32_e32 v2, 0
	s_addc_u32 s3, s14, s3
	s_mov_b32 s14, -2
	s_mov_b64 s[42:43], s[16:17]
	v_mov_b32_e32 v3, v2
	v_mov_b32_e32 v4, v2
	v_mov_b32_e32 v5, v2
	v_mov_b32_e32 v6, v2
	v_mov_b32_e32 v7, v2
	v_mov_b32_e32 v8, v2
	v_mov_b32_e32 v9, v2
	v_mov_b32_e32 v10, v2
	v_mov_b32_e32 v11, v2
	v_mov_b32_e32 v12, v2
	v_mov_b32_e32 v13, v2
	v_mov_b32_e32 v14, v2
	v_mov_b32_e32 v15, v2
	v_mov_b32_e32 v16, v2
	v_mov_b32_e32 v17, v2
	v_mov_b32_e32 v18, v2
	v_mov_b32_e32 v19, v2
	v_mov_b32_e32 v20, v2
	v_mov_b32_e32 v21, v2
	v_mov_b32_e32 v22, v2
	v_mov_b32_e32 v23, v2
	v_mov_b32_e32 v24, v2
	v_mov_b32_e32 v25, v2
	v_mov_b32_e32 v26, v2
	v_mov_b32_e32 v27, v2
	v_mov_b32_e32 v28, v2
	v_mov_b32_e32 v29, v2
	v_mov_b32_e32 v30, v2
	v_mov_b32_e32 v31, v2
	v_mov_b32_e32 v32, v2
	v_mov_b32_e32 v33, v2
	v_mov_b32_e32 v34, v2
	v_mov_b32_e32 v35, v2
	v_mov_b32_e32 v36, v2
	v_mov_b32_e32 v37, v2
	v_mov_b32_e32 v38, v2
	v_mov_b32_e32 v39, v2
	v_mov_b32_e32 v40, v2
	v_mov_b32_e32 v41, v2
	v_mov_b32_e32 v42, v2
	v_mov_b32_e32 v43, v2
	v_mov_b32_e32 v44, v2
	v_mov_b32_e32 v45, v2
	v_mov_b32_e32 v46, v2
	v_mov_b32_e32 v47, v2
	v_mov_b32_e32 v48, v2
	v_mov_b32_e32 v49, v2
	v_mov_b32_e32 v50, v2
	v_mov_b32_e32 v51, v2
	v_mov_b32_e32 v52, v2
	v_mov_b32_e32 v53, v2
	v_mov_b32_e32 v54, v2
	v_mov_b32_e32 v55, v2
	v_mov_b32_e32 v56, v2
	v_mov_b32_e32 v57, v2
	v_mov_b32_e32 v58, v2
	v_mov_b32_e32 v59, v2
	v_mov_b32_e32 v60, v2
	v_mov_b32_e32 v61, v2
	v_mov_b32_e32 v62, v2
	v_mov_b32_e32 v63, v2
	v_mov_b32_e32 v64, v2
	v_mov_b32_e32 v65, v2
	v_mov_b32_e32 v66, v2
	v_mov_b32_e32 v67, v2
	v_mov_b32_e32 v68, v2
	v_mov_b32_e32 v69, v2
	v_mov_b32_e32 v70, v2
	v_mov_b32_e32 v71, v2
	v_mov_b32_e32 v72, v2
	v_mov_b32_e32 v73, v2
	v_mov_b32_e32 v74, v2
	v_mov_b32_e32 v75, v2
	v_mov_b32_e32 v76, v2
	v_mov_b32_e32 v77, v2
	v_mov_b32_e32 v78, v2
	v_mov_b32_e32 v79, v2
	v_mov_b32_e32 v80, v2
	v_mov_b32_e32 v81, v2
	v_mov_b32_e32 v82, v2
	v_mov_b32_e32 v83, v2
	v_mov_b32_e32 v84, v2
	v_mov_b32_e32 v85, v2
	v_mov_b32_e32 v86, v2
	v_mov_b32_e32 v87, v2
	v_mov_b32_e32 v88, v2
	v_mov_b32_e32 v89, v2
	v_mov_b32_e32 v90, v2
	v_mov_b32_e32 v91, v2
	v_mov_b32_e32 v92, v2
	v_mov_b32_e32 v93, v2
	v_mov_b32_e32 v94, v2
	v_mov_b32_e32 v95, v2
	v_mov_b32_e32 v96, v2
	v_mov_b32_e32 v97, v2
	v_mov_b32_e32 v98, v2
	v_mov_b32_e32 v99, v2
	v_mov_b32_e32 v100, v2
	v_mov_b32_e32 v101, v2
	v_mov_b32_e32 v102, v2
	v_mov_b32_e32 v103, v2
	v_mov_b32_e32 v104, v2
	v_mov_b32_e32 v105, v2
	v_mov_b32_e32 v106, v2
	v_mov_b32_e32 v107, v2
	v_mov_b32_e32 v108, v2
	v_mov_b32_e32 v109, v2
	v_mov_b32_e32 v110, v2
	v_mov_b32_e32 v111, v2
	v_mov_b32_e32 v112, v2
	v_mov_b32_e32 v113, v2
	v_mov_b32_e32 v114, v2
	v_mov_b32_e32 v115, v2
	v_mov_b32_e32 v116, v2
	v_mov_b32_e32 v117, v2
	v_mov_b32_e32 v118, v2
	v_mov_b32_e32 v119, v2
	v_mov_b32_e32 v120, v2
	v_mov_b32_e32 v121, v2
	v_mov_b32_e32 v122, v2
	v_mov_b32_e32 v123, v2
	v_mov_b32_e32 v124, v2
	v_mov_b32_e32 v125, v2
	v_mov_b32_e32 v126, v2
	v_mov_b32_e32 v127, v2
	v_mov_b32_e32 v128, v2
	v_mov_b32_e32 v129, v2
	s_mov_b64 s[16:17], 0x16c29100
	s_mov_b64 s[18:19], 0x16c69100
	s_mov_b64 s[20:21], 0x16c29180
	s_barrier
